# P6 branch-GEMM gate hook and epilogue: serialized load-wait pairs replaced by batched loads via register ring
# speedup vs baseline: 1.0277x; 1.0277x over previous
; #define PG8_STAGE(bufoff, gbase, voff) do { _Pragma("unroll") for (int _i = 0; _i < 2; ++_i) \
;         __builtin_amdgcn_global_load_lds((const unsigned*)((const char*)(gbase) + (voff)[_i]), (LAS unsigned*)(lds + (bufoff) + ldsw + _i * 8192), 16, 0, 0); } while (0)
; #define PG8_LDA(dst, b, h) do { _Pragma("unroll") for (int m = 0; m < 4; ++m) _Pragma("unroll") for (int k = 0; k < 2; ++k) dst[m][k] = *(const LAS bf16x8*)(lds + PG8_SA(b, h) + aoff + m * 2048 + k * 1024); } while (0)
; #define PG8_LDB(dst, b, h) do { _Pragma("unroll") for (int n = 0; n < 2; ++n) _Pragma("unroll") for (int k = 0; k < 2; ++k) dst[n][k] = *(const LAS bf16x8*)(lds + PG8_SB(b, h) + boff + n * 2048 + k * 1024); } while (0)
; #define PG8_MMA(ai, bj, At, Bt) do { __builtin_amdgcn_s_setprio(1); _Pragma("unroll") for (int m = 0; m < 4; ++m) _Pragma("unroll") for (int n = 0; n < 2; ++n) _Pragma("unroll") for (int k = 0; k < 2; ++k) \
;         acc[ai][bj][m][n] = __builtin_amdgcn_mfma_f32_16x16x32_bf16(Bt[n][k], At[m][k], acc[ai][bj][m][n], 0, 0, 0); __builtin_amdgcn_s_setprio(0); } while (0)
; #define PG8_WAIT_V(n) asm volatile("s_waitcnt vmcnt(" #n ")" ::: "memory")
; #define PG8_WAIT_L(n) asm volatile("s_waitcnt lgkmcnt(" #n ")" ::: "memory")
; #define PG8_BAR __builtin_amdgcn_s_barrier()
; #define PG8_SCHED __builtin_amdgcn_sched_barrier(0)
; template <class Epi, class Sched>
; DI void gemm_phase(LAS unsigned char* lds, const int tid, const int K, const int lda, const int ldb, const Sched& S_, const Epi& E) {
;     ...
;             const bool last = (t == nt - 2);
;             const char* a1 = cA + (size_t)(t + 1) * kstep;
;             const char* a2 = last ? nA : cA + (size_t)(t + 2) * kstep; const char* b2 = last ? nB : cB + (size_t)(t + 2) * kstep;
;             const char* a3 = a2 + kstep; const char* b3 = b2 + kstep;
;             PG8_LDB(B0, 0, 0); PG8_LDB(B1, 0, 1); PG8_SCHED; PG8_LDA(At, 0, 0); PG8_STAGE(PG8_SA(1, 1), a1 + hstepA, voffA);
;             PG8_WAIT_V(8); PG8_WAIT_L(0); PG8_BAR; PG8_MMA(0, 0, At, B0); PG8_MMA(0, 1, At, B1); PG8_BAR; PG8_SCHED;
;             PG8_LDA(At, 0, 1); PG8_STAGE(PG8_SB(0, 0), b2, voffB); PG8_STAGE(PG8_SB(0, 1), b2 + hstepB, voffB); PG8_STAGE(PG8_SA(0, 0), a2, voffA);
;             PG8_WAIT_V(8); PG8_WAIT_L(0); PG8_BAR; PG8_MMA(1, 0, At, B0); PG8_MMA(1, 1, At, B1); PG8_BAR; PG8_SCHED;
.LBB0_713:
	s_add_u32 s14, s58, 0xfff80080
	s_addc_u32 s16, s59, -1
	s_add_i32 s29, 0, 0x10000
	s_cmpk_eq_i32 s60, 0x3c00
	s_cselect_b64 s[8:9], -1, 0
	s_and_b64 s[10:11], s[8:9], exec
	s_cselect_b32 s17, s55, s16
	s_cselect_b32 s16, s54, s14
	v_add_u32_e32 v128, s29, v155
	s_cselect_b32 s11, s57, s21
	s_cselect_b32 s10, s56, s20
	s_add_i32 s14, 0, 0x14000
	ds_read_b128 v[130:133], v128
	ds_read_b128 v[150:153], v128 offset:1024
	ds_read_b128 v[158:161], v128 offset:2048
	ds_read_b128 v[162:165], v128 offset:3072
	v_add_u32_e32 v128, s14, v155
	ds_read_b128 v[166:169], v128
	ds_read_b128 v[170:173], v128 offset:1024
	ds_read_b128 v[174:177], v128 offset:2048
	ds_read_b128 v[178:181], v128 offset:3072
	v_lshl_add_u64 v[214:215], s[58:59], 0, v[142:143]
	s_add_i32 m0, s2, 0xc000
	ds_read_b128 v[182:185], v157
	ds_read_b128 v[186:189], v157 offset:1024
	ds_read_b128 v[190:193], v157 offset:2048
	ds_read_b128 v[194:197], v157 offset:3072
	ds_read_b128 v[198:201], v157 offset:4096
	ds_read_b128 v[202:205], v157 offset:5120
	ds_read_b128 v[206:209], v157 offset:6144
	ds_read_b128 v[210:213], v157 offset:7168
	global_load_lds_dwordx4 v[214:215], off
	v_lshl_add_u64 v[214:215], s[58:59], 0, v[144:145]
	s_add_i32 m0, s2, 0xe000
	s_nop 0
	global_load_lds_dwordx4 v[214:215], off
	s_waitcnt vmcnt(8)
	s_waitcnt lgkmcnt(0)
	s_barrier
	s_setprio 1
	s_waitcnt lgkmcnt(0)
	v_mfma_f32_16x16x32_bf16 v[124:127], v[130:133], v[182:185], v[124:127]
	v_mfma_f32_16x16x32_bf16 v[120:123], v[158:161], v[182:185], v[120:123]
	v_mfma_f32_16x16x32_bf16 v[108:111], v[130:133], v[190:193], v[108:111]
	v_mfma_f32_16x16x32_bf16 v[104:107], v[158:161], v[190:193], v[104:107]
	v_mfma_f32_16x16x32_bf16 v[92:95], v[130:133], v[198:201], v[92:95]
	v_mfma_f32_16x16x32_bf16 v[88:91], v[158:161], v[198:201], v[88:91]
	v_mfma_f32_16x16x32_bf16 v[76:79], v[130:133], v[206:209], v[76:79]
	v_mfma_f32_16x16x32_bf16 v[72:75], v[158:161], v[206:209], v[72:75]
	v_mfma_f32_16x16x32_bf16 v[124:127], v[150:153], v[186:189], v[124:127]
	v_mfma_f32_16x16x32_bf16 v[120:123], v[162:165], v[186:189], v[120:123]
	v_mfma_f32_16x16x32_bf16 v[108:111], v[150:153], v[194:197], v[108:111]
	v_mfma_f32_16x16x32_bf16 v[104:107], v[162:165], v[194:197], v[104:107]
	v_mfma_f32_16x16x32_bf16 v[92:95], v[150:153], v[202:205], v[92:95]
	v_mfma_f32_16x16x32_bf16 v[88:91], v[162:165], v[202:205], v[88:91]
	v_mfma_f32_16x16x32_bf16 v[76:79], v[150:153], v[210:213], v[76:79]
	v_mfma_f32_16x16x32_bf16 v[72:75], v[162:165], v[210:213], v[72:75]
	s_setprio 0
	s_setprio 1
	v_mfma_f32_16x16x32_bf16 v[116:119], v[166:169], v[182:185], v[116:119]
	v_mfma_f32_16x16x32_bf16 v[112:115], v[174:177], v[182:185], v[112:115]
	v_mfma_f32_16x16x32_bf16 v[100:103], v[166:169], v[190:193], v[100:103]
	v_mfma_f32_16x16x32_bf16 v[96:99], v[174:177], v[190:193], v[96:99]
	v_mfma_f32_16x16x32_bf16 v[84:87], v[166:169], v[198:201], v[84:87]
	v_mfma_f32_16x16x32_bf16 v[80:83], v[174:177], v[198:201], v[80:83]
	v_mfma_f32_16x16x32_bf16 v[68:71], v[166:169], v[206:209], v[68:71]
	v_mfma_f32_16x16x32_bf16 v[64:67], v[174:177], v[206:209], v[64:67]
	v_mfma_f32_16x16x32_bf16 v[116:119], v[170:173], v[186:189], v[116:119]
	v_mfma_f32_16x16x32_bf16 v[112:115], v[178:181], v[186:189], v[112:115]
	v_mfma_f32_16x16x32_bf16 v[100:103], v[170:173], v[194:197], v[100:103]
	v_mfma_f32_16x16x32_bf16 v[96:99], v[178:181], v[194:197], v[96:99]
	v_mfma_f32_16x16x32_bf16 v[84:87], v[170:173], v[202:205], v[84:87]
	v_mfma_f32_16x16x32_bf16 v[80:83], v[178:181], v[202:205], v[80:83]
	v_mfma_f32_16x16x32_bf16 v[68:71], v[170:173], v[210:213], v[68:71]
	v_mfma_f32_16x16x32_bf16 v[64:67], v[178:181], v[210:213], v[64:67]
	s_setprio 0
	s_barrier
	s_add_i32 s29, s29, s97
	v_lshl_add_u64 v[214:215], s[10:11], 0, v[136:137]
	s_mov_b32 m0, s29
	ds_read_b128 v[182:185], v157 offset:16384
	ds_read_b128 v[186:189], v157 offset:17408
	ds_read_b128 v[190:193], v157 offset:18432
	ds_read_b128 v[194:197], v157 offset:19456
	ds_read_b128 v[198:201], v157 offset:20480
	ds_read_b128 v[202:205], v157 offset:21504
	ds_read_b128 v[206:209], v157 offset:22528
	ds_read_b128 v[210:213], v157 offset:23552
	global_load_lds_dwordx4 v[214:215], off
	s_add_i32 m0, s29, 0x2000
	s_add_u32 s30, s10, 0x80000
	v_lshl_add_u64 v[216:217], s[10:11], 0, v[140:141]
	s_addc_u32 s31, s11, 0
	s_add_i32 s14, s14, s97
	global_load_lds_dwordx4 v[216:217], off
	v_lshl_add_u64 v[222:223], s[30:31], 0, v[136:137]
	s_mov_b32 m0, s14
	v_lshl_add_u64 v[224:225], s[16:17], 0, v[138:139]
	global_load_lds_dwordx4 v[222:223], off
	v_lshl_add_u64 v[222:223], s[30:31], 0, v[140:141]
	s_add_i32 m0, s14, 0x2000
	s_nop 0
	global_load_lds_dwordx4 v[222:223], off
	v_lshl_add_u64 v[222:223], s[16:17], 0, v[134:135]
	s_mov_b32 m0, s2
	s_nop 0
	global_load_lds_dwordx4 v[222:223], off
	s_mov_b32 m0, s3
	s_nop 0
	global_load_lds_dwordx4 v[224:225], off
	s_waitcnt vmcnt(8)
	s_waitcnt lgkmcnt(0)
	s_barrier
; #define PG8_STAGE(bufoff, gbase, voff) do { _Pragma("unroll") for (int _i = 0; _i < 2; ++_i) \
;         __builtin_amdgcn_global_load_lds((const unsigned*)((const char*)(gbase) + (voff)[_i]), (LAS unsigned*)(lds + (bufoff) + ldsw + _i * 8192), 16, 0, 0); } while (0)
; #define PG8_LDA(dst, b, h) do { _Pragma("unroll") for (int m = 0; m < 4; ++m) _Pragma("unroll") for (int k = 0; k < 2; ++k) dst[m][k] = *(const LAS bf16x8*)(lds + PG8_SA(b, h) + aoff + m * 2048 + k * 1024); } while (0)
; #define PG8_LDB(dst, b, h) do { _Pragma("unroll") for (int n = 0; n < 2; ++n) _Pragma("unroll") for (int k = 0; k < 2; ++k) dst[n][k] = *(const LAS bf16x8*)(lds + PG8_SB(b, h) + boff + n * 2048 + k * 1024); } while (0)
; #define PG8_MMA(ai, bj, At, Bt) do { __builtin_amdgcn_s_setprio(1); _Pragma("unroll") for (int m = 0; m < 4; ++m) _Pragma("unroll") for (int n = 0; n < 2; ++n) _Pragma("unroll") for (int k = 0; k < 2; ++k) \
;         acc[ai][bj][m][n] = __builtin_amdgcn_mfma_f32_16x16x32_bf16(Bt[n][k], At[m][k], acc[ai][bj][m][n], 0, 0, 0); __builtin_amdgcn_s_setprio(0); } while (0)
; #define PG8_WAIT_V(n) asm volatile("s_waitcnt vmcnt(" #n ")" ::: "memory")
; #define PG8_WAIT_L(n) asm volatile("s_waitcnt lgkmcnt(" #n ")" ::: "memory")
; #define PG8_BAR __builtin_amdgcn_s_barrier()
; #define PG8_SCHED __builtin_amdgcn_sched_barrier(0)
; template <class Epi, class Sched>
; DI void gemm_phase(LAS unsigned char* lds, const int tid, const int K, const int lda, const int ldb, const Sched& S_, const Epi& E) {
;     ...
;             PG8_WAIT_V(8); PG8_WAIT_L(0); PG8_BAR; PG8_MMA(1, 0, At, B0); PG8_MMA(1, 1, At, B1); PG8_BAR; PG8_SCHED;
;             PG8_LDB(B0, 1, 0); PG8_LDB(B1, 1, 1); PG8_SCHED; PG8_LDA(At, 1, 0); PG8_STAGE(PG8_SA(0, 1), a2 + hstepA, voffA);
;             PG8_WAIT_V(8); PG8_WAIT_L(0); PG8_BAR; PG8_MMA(0, 0, At, B0); PG8_MMA(0, 1, At, B1); PG8_BAR; PG8_SCHED;
	s_setprio 1
	s_waitcnt lgkmcnt(0)
	v_mfma_f32_16x16x32_bf16 v[60:63], v[130:133], v[182:185], v[60:63]
	v_mfma_f32_16x16x32_bf16 v[56:59], v[158:161], v[182:185], v[56:59]
	v_mfma_f32_16x16x32_bf16 v[44:47], v[130:133], v[190:193], v[44:47]
	v_mfma_f32_16x16x32_bf16 v[40:43], v[158:161], v[190:193], v[40:43]
	v_mfma_f32_16x16x32_bf16 v[28:31], v[130:133], v[198:201], v[28:31]
	v_mfma_f32_16x16x32_bf16 v[24:27], v[158:161], v[198:201], v[24:27]
	v_mfma_f32_16x16x32_bf16 v[12:15], v[130:133], v[206:209], v[12:15]
	v_mfma_f32_16x16x32_bf16 v[8:11], v[158:161], v[206:209], v[8:11]
	v_mfma_f32_16x16x32_bf16 v[60:63], v[150:153], v[186:189], v[60:63]
	v_mfma_f32_16x16x32_bf16 v[56:59], v[162:165], v[186:189], v[56:59]
	v_mfma_f32_16x16x32_bf16 v[44:47], v[150:153], v[194:197], v[44:47]
	v_mfma_f32_16x16x32_bf16 v[40:43], v[162:165], v[194:197], v[40:43]
	v_mfma_f32_16x16x32_bf16 v[28:31], v[150:153], v[202:205], v[28:31]
	v_mfma_f32_16x16x32_bf16 v[24:27], v[162:165], v[202:205], v[24:27]
	v_mfma_f32_16x16x32_bf16 v[12:15], v[150:153], v[210:213], v[12:15]
	v_mfma_f32_16x16x32_bf16 v[8:11], v[162:165], v[210:213], v[8:11]
	s_setprio 0
	s_setprio 1
	v_mfma_f32_16x16x32_bf16 v[52:55], v[166:169], v[182:185], v[52:55]
	v_mfma_f32_16x16x32_bf16 v[48:51], v[174:177], v[182:185], v[48:51]
	v_mfma_f32_16x16x32_bf16 v[36:39], v[166:169], v[190:193], v[36:39]
	v_mfma_f32_16x16x32_bf16 v[32:35], v[174:177], v[190:193], v[32:35]
	v_mfma_f32_16x16x32_bf16 v[20:23], v[166:169], v[198:201], v[20:23]
	v_mfma_f32_16x16x32_bf16 v[16:19], v[174:177], v[198:201], v[16:19]
	v_mfma_f32_16x16x32_bf16 v[4:7], v[166:169], v[206:209], v[4:7]
	v_mfma_f32_16x16x32_bf16 v[0:3], v[174:177], v[206:209], v[0:3]
	v_mfma_f32_16x16x32_bf16 v[52:55], v[170:173], v[186:189], v[52:55]
	v_mfma_f32_16x16x32_bf16 v[48:51], v[178:181], v[186:189], v[48:51]
	v_mfma_f32_16x16x32_bf16 v[36:39], v[170:173], v[194:197], v[36:39]
	v_mfma_f32_16x16x32_bf16 v[32:35], v[178:181], v[194:197], v[32:35]
	v_mfma_f32_16x16x32_bf16 v[20:23], v[170:173], v[202:205], v[20:23]
	v_mfma_f32_16x16x32_bf16 v[16:19], v[178:181], v[202:205], v[16:19]
	v_mfma_f32_16x16x32_bf16 v[4:7], v[170:173], v[210:213], v[4:7]
	v_mfma_f32_16x16x32_bf16 v[0:3], v[178:181], v[210:213], v[0:3]
	s_setprio 0
	s_barrier
	s_add_i32 s14, 0, 0x18000
	v_add_u32_e32 v128, s14, v155
	s_add_i32 s29, 0, 0x1c000
	ds_read_b128 v[130:133], v128
	ds_read_b128 v[150:153], v128 offset:1024
	ds_read_b128 v[158:161], v128 offset:2048
	ds_read_b128 v[162:165], v128 offset:3072
	v_add_u32_e32 v128, s29, v155
	ds_read_b128 v[166:169], v128
	ds_read_b128 v[170:173], v128 offset:1024
	ds_read_b128 v[174:177], v128 offset:2048
	ds_read_b128 v[178:181], v128 offset:3072
	s_add_u32 s16, s16, 0x80000
	s_addc_u32 s17, s17, 0
	s_mov_b32 m0, s78
	v_lshl_add_u64 v[226:227], s[16:17], 0, v[134:135]
	ds_read_b128 v[182:185], v157 offset:32768
	ds_read_b128 v[186:189], v157 offset:33792
	ds_read_b128 v[190:193], v157 offset:34816
	ds_read_b128 v[194:197], v157 offset:35840
	ds_read_b128 v[198:201], v157 offset:36864
	ds_read_b128 v[202:205], v157 offset:37888
	ds_read_b128 v[206:209], v157 offset:38912
	ds_read_b128 v[210:213], v157 offset:39936
	global_load_lds_dwordx4 v[226:227], off
	v_lshl_add_u64 v[226:227], s[16:17], 0, v[138:139]
	s_mov_b32 m0, s79
	s_nop 0
	global_load_lds_dwordx4 v[226:227], off
	s_waitcnt vmcnt(8)
	s_waitcnt lgkmcnt(0)
	s_barrier
	s_setprio 1
	s_waitcnt lgkmcnt(0)
	v_mfma_f32_16x16x32_bf16 v[124:127], v[130:133], v[182:185], v[124:127]
	v_mfma_f32_16x16x32_bf16 v[120:123], v[158:161], v[182:185], v[120:123]
	v_mfma_f32_16x16x32_bf16 v[108:111], v[130:133], v[190:193], v[108:111]
	v_mfma_f32_16x16x32_bf16 v[104:107], v[158:161], v[190:193], v[104:107]
	v_mfma_f32_16x16x32_bf16 v[92:95], v[130:133], v[198:201], v[92:95]
	v_mfma_f32_16x16x32_bf16 v[88:91], v[158:161], v[198:201], v[88:91]
	v_mfma_f32_16x16x32_bf16 v[76:79], v[130:133], v[206:209], v[76:79]
	v_mfma_f32_16x16x32_bf16 v[72:75], v[158:161], v[206:209], v[72:75]
	v_mfma_f32_16x16x32_bf16 v[124:127], v[150:153], v[186:189], v[124:127]
	v_mfma_f32_16x16x32_bf16 v[120:123], v[162:165], v[186:189], v[120:123]
	v_mfma_f32_16x16x32_bf16 v[108:111], v[150:153], v[194:197], v[108:111]
	v_mfma_f32_16x16x32_bf16 v[104:107], v[162:165], v[194:197], v[104:107]
	v_mfma_f32_16x16x32_bf16 v[92:95], v[150:153], v[202:205], v[92:95]
	v_mfma_f32_16x16x32_bf16 v[88:91], v[162:165], v[202:205], v[88:91]
	v_mfma_f32_16x16x32_bf16 v[76:79], v[150:153], v[210:213], v[76:79]
	v_mfma_f32_16x16x32_bf16 v[72:75], v[162:165], v[210:213], v[72:75]
	s_setprio 0
	s_setprio 1
	v_mfma_f32_16x16x32_bf16 v[116:119], v[166:169], v[182:185], v[116:119]
	v_mfma_f32_16x16x32_bf16 v[112:115], v[174:177], v[182:185], v[112:115]
	v_mfma_f32_16x16x32_bf16 v[100:103], v[166:169], v[190:193], v[100:103]
	v_mfma_f32_16x16x32_bf16 v[96:99], v[174:177], v[190:193], v[96:99]
	v_mfma_f32_16x16x32_bf16 v[84:87], v[166:169], v[198:201], v[84:87]
	v_mfma_f32_16x16x32_bf16 v[80:83], v[174:177], v[198:201], v[80:83]
	v_mfma_f32_16x16x32_bf16 v[68:71], v[166:169], v[206:209], v[68:71]
	v_mfma_f32_16x16x32_bf16 v[64:67], v[174:177], v[206:209], v[64:67]
	v_mfma_f32_16x16x32_bf16 v[116:119], v[170:173], v[186:189], v[116:119]
	v_mfma_f32_16x16x32_bf16 v[112:115], v[178:181], v[186:189], v[112:115]
	v_mfma_f32_16x16x32_bf16 v[100:103], v[170:173], v[194:197], v[100:103]
	v_mfma_f32_16x16x32_bf16 v[96:99], v[178:181], v[194:197], v[96:99]
	v_mfma_f32_16x16x32_bf16 v[84:87], v[170:173], v[202:205], v[84:87]
	v_mfma_f32_16x16x32_bf16 v[80:83], v[178:181], v[202:205], v[80:83]
	v_mfma_f32_16x16x32_bf16 v[68:71], v[170:173], v[210:213], v[68:71]
	v_mfma_f32_16x16x32_bf16 v[64:67], v[178:181], v[210:213], v[64:67]
	s_setprio 0
	s_barrier
; DI void unpack8(const u32x4 v, float* x) { x[0] = bflo(v.x); x[1] = bfhi(v.x); x[2] = bflo(v.y); x[3] = bfhi(v.y); x[4] = bflo(v.z); x[5] = bfhi(v.z); x[6] = bflo(v.w); x[7] = bfhi(v.w); }
; #define PG8_STAGE(bufoff, gbase, voff) do { _Pragma("unroll") for (int _i = 0; _i < 2; ++_i) \
;         __builtin_amdgcn_global_load_lds((const unsigned*)((const char*)(gbase) + (voff)[_i]), (LAS unsigned*)(lds + (bufoff) + ldsw + _i * 8192), 16, 0, 0); } while (0)
;     DI void hook(f32x4 (&acc)[2][2][4][2], const Unit& u, int n, int wr, int wc, int fr, int fq) const {
;         int row0 = u.pm * BM + wr * 64 + fr, col0 = u.pn * BM + wc * 32 + 8 * fq;
;         asm volatile("" : "+v"(row0), "+v"(col0));
; #pragma unroll
;         for (int ai = 0; ai < 2; ++ai) {
; #pragma unroll
;             for (int m = 0; m < 4; ++m) { const size_t row = (size_t)(row0 + ai * HALF + m * 16);
; #pragma unroll
;                 for (int bj = 0; bj < 2; ++bj) { const int col = col0 + bj * HALF;
;                     float gp[8], gc[8]; unpack8(*(const u32x4*)(G + row * LDP + (size_t)(n - 1) * DM + col), gp); unpack8(*(const u32x4*)(G + row * LDP + (size_t)n * DM + col), gc);
; #pragma unroll
;                     for (int j = 0; j < 4; ++j) { acc[ai][bj][m][0][j] *= fmaxf(gp[j], 1e-30f) * __builtin_amdgcn_rcpf(fmaxf(gc[j], 1e-30f));
;                                                   acc[ai][bj][m][1][j] *= fmaxf(gp[4 + j], 1e-30f) * __builtin_amdgcn_rcpf(fmaxf(gc[4 + j], 1e-30f)); } }
;                 if (m & 1) asm volatile("" ::: "memory"); }
; template <class Epi, class Sched>
; DI void gemm_phase(LAS unsigned char* lds, const int tid, const int K, const int lda, const int ldb, const Sched& S_, const Epi& E) {
;     ...
;             PG8_LDB(B0, 1, 0); PG8_LDB(B1, 1, 1); PG8_SCHED; PG8_LDA(At, 1, 0); PG8_STAGE(PG8_SA(0, 1), a2 + hstepA, voffA);
;             PG8_WAIT_V(8); PG8_WAIT_L(0); PG8_BAR; PG8_MMA(0, 0, At, B0); PG8_MMA(0, 1, At, B1); PG8_BAR; PG8_SCHED;
;             PG8_LDA(At, 1, 1); PG8_STAGE(PG8_SB(1, 0), b3, voffB); PG8_STAGE(PG8_SB(1, 1), b3 + hstepB, voffB); PG8_STAGE(PG8_SA(1, 0), a3, voffA);
;             PG8_WAIT_V(8); PG8_WAIT_L(0); PG8_BAR; PG8_MMA(1, 0, At, B0); PG8_MMA(1, 1, At, B1); PG8_BAR; PG8_SCHED;
;             if constexpr (Epi::HOOK) { if (((t + 2) & 7) == 0 && !last) { E.hook(acc, cur, (t + 2) >> 3, wr, wc, fr, fq); PG8_SCHED; } }
	s_add_i32 s14, s14, s97
	v_lshl_add_u64 v[214:215], v[214:215], 0, s[94:95]
	s_mov_b32 m0, s14
	ds_read_b128 v[182:185], v157 offset:49152
	ds_read_b128 v[186:189], v157 offset:50176
	ds_read_b128 v[190:193], v157 offset:51200
	ds_read_b128 v[194:197], v157 offset:52224
	ds_read_b128 v[198:201], v157 offset:53248
	ds_read_b128 v[202:205], v157 offset:54272
	ds_read_b128 v[206:209], v157 offset:55296
	ds_read_b128 v[210:213], v157 offset:56320
	global_load_lds_dwordx4 v[214:215], off
	s_add_i32 m0, s14, 0x2000
	s_add_u32 s10, s10, 0x80080
	v_lshl_add_u64 v[214:215], v[216:217], 0, s[94:95]
	s_addc_u32 s11, s11, 0
	s_add_i32 s14, s29, s97
	global_load_lds_dwordx4 v[214:215], off
	v_lshl_add_u64 v[214:215], s[10:11], 0, v[136:137]
	s_mov_b32 m0, s14
	s_nop 0
	global_load_lds_dwordx4 v[214:215], off
	v_lshl_add_u64 v[214:215], s[10:11], 0, v[140:141]
	s_add_i32 m0, s14, 0x2000
	s_nop 0
	global_load_lds_dwordx4 v[214:215], off
	v_lshl_add_u64 v[214:215], v[222:223], 0, s[94:95]
	s_mov_b32 m0, s80
	s_nop 0
	global_load_lds_dwordx4 v[214:215], off
	v_lshl_add_u64 v[214:215], v[224:225], 0, s[94:95]
	s_mov_b32 m0, s81
	s_nop 0
	global_load_lds_dwordx4 v[214:215], off
	s_waitcnt vmcnt(8)
	s_waitcnt lgkmcnt(0)
	s_barrier
	s_setprio 1
	s_waitcnt lgkmcnt(0)
	v_mfma_f32_16x16x32_bf16 v[60:63], v[130:133], v[182:185], v[60:63]
	v_mfma_f32_16x16x32_bf16 v[56:59], v[158:161], v[182:185], v[56:59]
	v_mfma_f32_16x16x32_bf16 v[44:47], v[130:133], v[190:193], v[44:47]
	v_mfma_f32_16x16x32_bf16 v[40:43], v[158:161], v[190:193], v[40:43]
	v_mfma_f32_16x16x32_bf16 v[28:31], v[130:133], v[198:201], v[28:31]
	v_mfma_f32_16x16x32_bf16 v[24:27], v[158:161], v[198:201], v[24:27]
	v_mfma_f32_16x16x32_bf16 v[12:15], v[130:133], v[206:209], v[12:15]
	v_mfma_f32_16x16x32_bf16 v[8:11], v[158:161], v[206:209], v[8:11]
	v_mfma_f32_16x16x32_bf16 v[60:63], v[150:153], v[186:189], v[60:63]
	v_mfma_f32_16x16x32_bf16 v[56:59], v[162:165], v[186:189], v[56:59]
	v_mfma_f32_16x16x32_bf16 v[44:47], v[150:153], v[194:197], v[44:47]
	v_mfma_f32_16x16x32_bf16 v[40:43], v[162:165], v[194:197], v[40:43]
	v_mfma_f32_16x16x32_bf16 v[28:31], v[150:153], v[202:205], v[28:31]
	v_mfma_f32_16x16x32_bf16 v[24:27], v[162:165], v[202:205], v[24:27]
	v_mfma_f32_16x16x32_bf16 v[12:15], v[150:153], v[210:213], v[12:15]
	v_mfma_f32_16x16x32_bf16 v[8:11], v[162:165], v[210:213], v[8:11]
	s_setprio 0
	s_setprio 1
	v_mfma_f32_16x16x32_bf16 v[52:55], v[166:169], v[182:185], v[52:55]
	v_mfma_f32_16x16x32_bf16 v[48:51], v[174:177], v[182:185], v[48:51]
	v_mfma_f32_16x16x32_bf16 v[36:39], v[166:169], v[190:193], v[36:39]
	v_mfma_f32_16x16x32_bf16 v[32:35], v[174:177], v[190:193], v[32:35]
	v_mfma_f32_16x16x32_bf16 v[20:23], v[166:169], v[198:201], v[20:23]
	v_mfma_f32_16x16x32_bf16 v[16:19], v[174:177], v[198:201], v[16:19]
	v_mfma_f32_16x16x32_bf16 v[4:7], v[166:169], v[206:209], v[4:7]
	v_mfma_f32_16x16x32_bf16 v[0:3], v[174:177], v[206:209], v[0:3]
	v_mfma_f32_16x16x32_bf16 v[52:55], v[170:173], v[186:189], v[52:55]
	v_mfma_f32_16x16x32_bf16 v[48:51], v[178:181], v[186:189], v[48:51]
	v_mfma_f32_16x16x32_bf16 v[36:39], v[170:173], v[194:197], v[36:39]
	v_mfma_f32_16x16x32_bf16 v[32:35], v[178:181], v[194:197], v[32:35]
	v_mfma_f32_16x16x32_bf16 v[20:23], v[170:173], v[202:205], v[20:23]
	v_mfma_f32_16x16x32_bf16 v[16:19], v[178:181], v[202:205], v[16:19]
	v_mfma_f32_16x16x32_bf16 v[4:7], v[170:173], v[210:213], v[4:7]
	v_mfma_f32_16x16x32_bf16 v[0:3], v[178:181], v[210:213], v[0:3]
	s_setprio 0
	s_barrier
	s_add_i32 s10, s51, 4
	s_and_b32 s11, s10, 6
	s_cmp_lg_u32 s11, 0
	s_cselect_b64 s[16:17], -1, 0
	s_or_b64 s[8:9], s[8:9], s[16:17]
	s_and_b64 vcc, exec, s[8:9]
	s_cbranch_vccnz .LBB0_712
	s_lshr_b32 s14, s10, 3
	s_lshl_b32 s14, s14, 12
	s_add_u32 s8, s18, s14
	s_addc_u32 s9, s19, 0
	s_add_u32 s8, s8, 0xfffff800
	s_addc_u32 s9, s9, -1
	s_mov_b32 s62, 0xda24260
	s_mov_b32 s63, 0xffff0000
	s_mov_b32 s30, 0x8c000
	s_mov_b32 s31, 0
	s_mov_b32 s16, 0x2bc000
	s_mov_b32 s17, 0
	v_mov_b64_e32 v[132:133], s[8:9]
	v_mad_i64_i32 v[130:131], vcc, v146, s68, v[132:133]
	v_lshlrev_b32_e32 v132, 1, v148
	v_mov_b32_e32 v133, 0
	v_lshl_add_u64 v[130:131], v[130:131], 0, v[132:133]
	global_load_dwordx4 v[158:161], v[130:131], off offset:-2048
	global_load_dwordx4 v[162:165], v[130:131], off offset:2048
	global_load_dwordx4 v[166:169], v[130:131], off offset:-1792
	global_load_dwordx4 v[170:173], v[130:131], off offset:2304
	v_lshl_add_u64 v[130:131], v[130:131], 0, s[30:31]
	global_load_dwordx4 v[174:177], v[130:131], off offset:-2048
	global_load_dwordx4 v[178:181], v[130:131], off offset:2048
	global_load_dwordx4 v[182:185], v[130:131], off offset:-1792
	global_load_dwordx4 v[186:189], v[130:131], off offset:2304
	v_lshl_add_u64 v[130:131], v[130:131], 0, s[30:31]
	global_load_dwordx4 v[190:193], v[130:131], off offset:-2048
	global_load_dwordx4 v[194:197], v[130:131], off offset:2048
	global_load_dwordx4 v[198:201], v[130:131], off offset:-1792
	global_load_dwordx4 v[202:205], v[130:131], off offset:2304
	v_lshl_add_u64 v[130:131], v[130:131], 0, s[30:31]
	s_waitcnt vmcnt(10)
; DI void unpack8(const u32x4 v, float* x) { x[0] = bflo(v.x); x[1] = bfhi(v.x); x[2] = bflo(v.y); x[3] = bfhi(v.y); x[4] = bflo(v.z); x[5] = bfhi(v.z); x[6] = bflo(v.w); x[7] = bfhi(v.w); }
;     DI void hook(f32x4 (&acc)[2][2][4][2], const Unit& u, int n, int wr, int wc, int fr, int fq) const {
;         int row0 = u.pm * BM + wr * 64 + fr, col0 = u.pn * BM + wc * 32 + 8 * fq;
;         asm volatile("" : "+v"(row0), "+v"(col0));
; #pragma unroll
;         for (int ai = 0; ai < 2; ++ai) {
; #pragma unroll
;             for (int m = 0; m < 4; ++m) { const size_t row = (size_t)(row0 + ai * HALF + m * 16);
; #pragma unroll
;                 for (int bj = 0; bj < 2; ++bj) { const int col = col0 + bj * HALF;
;                     float gp[8], gc[8]; unpack8(*(const u32x4*)(G + row * LDP + (size_t)(n - 1) * DM + col), gp); unpack8(*(const u32x4*)(G + row * LDP + (size_t)n * DM + col), gc);
; #pragma unroll
;                     for (int j = 0; j < 4; ++j) { acc[ai][bj][m][0][j] *= fmaxf(gp[j], 1e-30f) * __builtin_amdgcn_rcpf(fmaxf(gc[j], 1e-30f));
;                                                   acc[ai][bj][m][1][j] *= fmaxf(gp[4 + j], 1e-30f) * __builtin_amdgcn_rcpf(fmaxf(gc[4 + j], 1e-30f)); } }
;                 if (m & 1) asm volatile("" ::: "memory"); }
	v_lshlrev_b32_e32 v206, 16, v158
	v_and_b32_e32 v207, s63, v158
	v_lshlrev_b32_e32 v214, 16, v162
	v_and_b32_e32 v215, s63, v162
	v_lshlrev_b32_e32 v208, 16, v159
	v_and_b32_e32 v209, s63, v159
	v_lshlrev_b32_e32 v216, 16, v163
	v_and_b32_e32 v217, s63, v163
	v_lshlrev_b32_e32 v210, 16, v160
	v_and_b32_e32 v211, s63, v160
	v_lshlrev_b32_e32 v222, 16, v164
	v_and_b32_e32 v223, s63, v164
	v_lshlrev_b32_e32 v212, 16, v161
	v_and_b32_e32 v213, s63, v161
	v_lshlrev_b32_e32 v224, 16, v165
	v_and_b32_e32 v225, s63, v165
	v_max_f32_e32 v214, s62, v214
	v_max_f32_e32 v215, s62, v215
	v_max_f32_e32 v216, s62, v216
	v_max_f32_e32 v217, s62, v217
	v_max_f32_e32 v222, s62, v222
	v_max_f32_e32 v223, s62, v223
	v_max_f32_e32 v224, s62, v224
	v_max_f32_e32 v225, s62, v225
	v_rcp_f32_e32 v214, v214
	v_rcp_f32_e32 v215, v215
	v_rcp_f32_e32 v216, v216
	v_rcp_f32_e32 v217, v217
	v_rcp_f32_e32 v222, v222
	v_rcp_f32_e32 v223, v223
	v_rcp_f32_e32 v224, v224
	v_rcp_f32_e32 v225, v225
	v_max_f32_e32 v206, s62, v206
	v_max_f32_e32 v207, s62, v207
	v_max_f32_e32 v208, s62, v208
	v_max_f32_e32 v209, s62, v209
	v_max_f32_e32 v210, s62, v210
	v_max_f32_e32 v211, s62, v211
	v_max_f32_e32 v212, s62, v212
	v_max_f32_e32 v213, s62, v213
	v_pk_mul_f32 v[206:207], v[206:207], v[214:215]
	v_pk_mul_f32 v[208:209], v[208:209], v[216:217]
	v_pk_mul_f32 v[210:211], v[210:211], v[222:223]
	v_pk_mul_f32 v[212:213], v[212:213], v[224:225]
	v_pk_mul_f32 v[124:125], v[124:125], v[206:207]
	v_pk_mul_f32 v[126:127], v[126:127], v[208:209]
	v_pk_mul_f32 v[120:121], v[120:121], v[210:211]
	v_pk_mul_f32 v[122:123], v[122:123], v[212:213]
	s_waitcnt vmcnt(8)
	v_lshlrev_b32_e32 v206, 16, v166
	v_and_b32_e32 v207, s63, v166
	v_lshlrev_b32_e32 v214, 16, v170
	v_and_b32_e32 v215, s63, v170
	v_lshlrev_b32_e32 v208, 16, v167
	v_and_b32_e32 v209, s63, v167
	v_lshlrev_b32_e32 v216, 16, v171
	v_and_b32_e32 v217, s63, v171
	v_lshlrev_b32_e32 v210, 16, v168
	v_and_b32_e32 v211, s63, v168
	v_lshlrev_b32_e32 v222, 16, v172
	v_and_b32_e32 v223, s63, v172
	v_lshlrev_b32_e32 v212, 16, v169
	v_and_b32_e32 v213, s63, v169
	v_lshlrev_b32_e32 v224, 16, v173
	v_and_b32_e32 v225, s63, v173
	v_max_f32_e32 v214, s62, v214
	v_max_f32_e32 v215, s62, v215
	v_max_f32_e32 v216, s62, v216
	v_max_f32_e32 v217, s62, v217
	v_max_f32_e32 v222, s62, v222
	v_max_f32_e32 v223, s62, v223
	v_max_f32_e32 v224, s62, v224
	v_max_f32_e32 v225, s62, v225
	v_rcp_f32_e32 v214, v214
	v_rcp_f32_e32 v215, v215
	v_rcp_f32_e32 v216, v216
	v_rcp_f32_e32 v217, v217
	v_rcp_f32_e32 v222, v222
	v_rcp_f32_e32 v223, v223
	v_rcp_f32_e32 v224, v224
	v_rcp_f32_e32 v225, v225
	v_max_f32_e32 v206, s62, v206
	v_max_f32_e32 v207, s62, v207
	v_max_f32_e32 v208, s62, v208
	v_max_f32_e32 v209, s62, v209
	v_max_f32_e32 v210, s62, v210
	v_max_f32_e32 v211, s62, v211
	v_max_f32_e32 v212, s62, v212
	v_max_f32_e32 v213, s62, v213
	v_pk_mul_f32 v[206:207], v[206:207], v[214:215]
	v_pk_mul_f32 v[208:209], v[208:209], v[216:217]
	v_pk_mul_f32 v[210:211], v[210:211], v[222:223]
	v_pk_mul_f32 v[212:213], v[212:213], v[224:225]
	v_pk_mul_f32 v[116:117], v[116:117], v[206:207]
	v_pk_mul_f32 v[118:119], v[118:119], v[208:209]
	v_pk_mul_f32 v[112:113], v[112:113], v[210:211]
	v_pk_mul_f32 v[114:115], v[114:115], v[212:213]
	global_load_dwordx4 v[158:161], v[130:131], off offset:-2048
	global_load_dwordx4 v[162:165], v[130:131], off offset:2048
	global_load_dwordx4 v[166:169], v[130:131], off offset:-1792
	global_load_dwordx4 v[170:173], v[130:131], off offset:2304
	v_lshl_add_u64 v[130:131], v[130:131], 0, s[16:17]
	s_waitcnt vmcnt(10)
	v_lshlrev_b32_e32 v206, 16, v174
	v_and_b32_e32 v207, s63, v174
	v_lshlrev_b32_e32 v214, 16, v178
	v_and_b32_e32 v215, s63, v178
	v_lshlrev_b32_e32 v208, 16, v175
	v_and_b32_e32 v209, s63, v175
	v_lshlrev_b32_e32 v216, 16, v179
	v_and_b32_e32 v217, s63, v179
	v_lshlrev_b32_e32 v210, 16, v176
	v_and_b32_e32 v211, s63, v176
	v_lshlrev_b32_e32 v222, 16, v180
	v_and_b32_e32 v223, s63, v180
	v_lshlrev_b32_e32 v212, 16, v177
	v_and_b32_e32 v213, s63, v177
	v_lshlrev_b32_e32 v224, 16, v181
	v_and_b32_e32 v225, s63, v181
	v_max_f32_e32 v214, s62, v214
	v_max_f32_e32 v215, s62, v215
	v_max_f32_e32 v216, s62, v216
	v_max_f32_e32 v217, s62, v217
	v_max_f32_e32 v222, s62, v222
	v_max_f32_e32 v223, s62, v223
	v_max_f32_e32 v224, s62, v224
	v_max_f32_e32 v225, s62, v225
	v_rcp_f32_e32 v214, v214
	v_rcp_f32_e32 v215, v215
	v_rcp_f32_e32 v216, v216
	v_rcp_f32_e32 v217, v217
	v_rcp_f32_e32 v222, v222
	v_rcp_f32_e32 v223, v223
	v_rcp_f32_e32 v224, v224
	v_rcp_f32_e32 v225, v225
	v_max_f32_e32 v206, s62, v206
	v_max_f32_e32 v207, s62, v207
	v_max_f32_e32 v208, s62, v208
	v_max_f32_e32 v209, s62, v209
	v_max_f32_e32 v210, s62, v210
	v_max_f32_e32 v211, s62, v211
	v_max_f32_e32 v212, s62, v212
	v_max_f32_e32 v213, s62, v213
	v_pk_mul_f32 v[206:207], v[206:207], v[214:215]
	v_pk_mul_f32 v[208:209], v[208:209], v[216:217]
	v_pk_mul_f32 v[210:211], v[210:211], v[222:223]
	v_pk_mul_f32 v[212:213], v[212:213], v[224:225]
	v_pk_mul_f32 v[108:109], v[108:109], v[206:207]
	v_pk_mul_f32 v[110:111], v[110:111], v[208:209]
	v_pk_mul_f32 v[104:105], v[104:105], v[210:211]
	v_pk_mul_f32 v[106:107], v[106:107], v[212:213]
	s_waitcnt vmcnt(8)
; DI void unpack8(const u32x4 v, float* x) { x[0] = bflo(v.x); x[1] = bfhi(v.x); x[2] = bflo(v.y); x[3] = bfhi(v.y); x[4] = bflo(v.z); x[5] = bfhi(v.z); x[6] = bflo(v.w); x[7] = bfhi(v.w); }
;     DI void hook(f32x4 (&acc)[2][2][4][2], const Unit& u, int n, int wr, int wc, int fr, int fq) const {
;         int row0 = u.pm * BM + wr * 64 + fr, col0 = u.pn * BM + wc * 32 + 8 * fq;
;         asm volatile("" : "+v"(row0), "+v"(col0));
; #pragma unroll
;         for (int ai = 0; ai < 2; ++ai) {
; #pragma unroll
;             for (int m = 0; m < 4; ++m) { const size_t row = (size_t)(row0 + ai * HALF + m * 16);
; #pragma unroll
;                 for (int bj = 0; bj < 2; ++bj) { const int col = col0 + bj * HALF;
;                     float gp[8], gc[8]; unpack8(*(const u32x4*)(G + row * LDP + (size_t)(n - 1) * DM + col), gp); unpack8(*(const u32x4*)(G + row * LDP + (size_t)n * DM + col), gc);
; #pragma unroll
;                     for (int j = 0; j < 4; ++j) { acc[ai][bj][m][0][j] *= fmaxf(gp[j], 1e-30f) * __builtin_amdgcn_rcpf(fmaxf(gc[j], 1e-30f));
;                                                   acc[ai][bj][m][1][j] *= fmaxf(gp[4 + j], 1e-30f) * __builtin_amdgcn_rcpf(fmaxf(gc[4 + j], 1e-30f)); } }
;                 if (m & 1) asm volatile("" ::: "memory"); }
	v_lshlrev_b32_e32 v206, 16, v182
	v_and_b32_e32 v207, s63, v182
	v_lshlrev_b32_e32 v214, 16, v186
	v_and_b32_e32 v215, s63, v186
	v_lshlrev_b32_e32 v208, 16, v183
	v_and_b32_e32 v209, s63, v183
	v_lshlrev_b32_e32 v216, 16, v187
	v_and_b32_e32 v217, s63, v187
	v_lshlrev_b32_e32 v210, 16, v184
	v_and_b32_e32 v211, s63, v184
	v_lshlrev_b32_e32 v222, 16, v188
	v_and_b32_e32 v223, s63, v188
	v_lshlrev_b32_e32 v212, 16, v185
	v_and_b32_e32 v213, s63, v185
	v_lshlrev_b32_e32 v224, 16, v189
	v_and_b32_e32 v225, s63, v189
	v_max_f32_e32 v214, s62, v214
	v_max_f32_e32 v215, s62, v215
	v_max_f32_e32 v216, s62, v216
	v_max_f32_e32 v217, s62, v217
	v_max_f32_e32 v222, s62, v222
	v_max_f32_e32 v223, s62, v223
	v_max_f32_e32 v224, s62, v224
	v_max_f32_e32 v225, s62, v225
	v_rcp_f32_e32 v214, v214
	v_rcp_f32_e32 v215, v215
	v_rcp_f32_e32 v216, v216
	v_rcp_f32_e32 v217, v217
	v_rcp_f32_e32 v222, v222
	v_rcp_f32_e32 v223, v223
	v_rcp_f32_e32 v224, v224
	v_rcp_f32_e32 v225, v225
	v_max_f32_e32 v206, s62, v206
	v_max_f32_e32 v207, s62, v207
	v_max_f32_e32 v208, s62, v208
	v_max_f32_e32 v209, s62, v209
	v_max_f32_e32 v210, s62, v210
	v_max_f32_e32 v211, s62, v211
	v_max_f32_e32 v212, s62, v212
	v_max_f32_e32 v213, s62, v213
	v_pk_mul_f32 v[206:207], v[206:207], v[214:215]
	v_pk_mul_f32 v[208:209], v[208:209], v[216:217]
	v_pk_mul_f32 v[210:211], v[210:211], v[222:223]
	v_pk_mul_f32 v[212:213], v[212:213], v[224:225]
	v_pk_mul_f32 v[100:101], v[100:101], v[206:207]
	v_pk_mul_f32 v[102:103], v[102:103], v[208:209]
	v_pk_mul_f32 v[96:97], v[96:97], v[210:211]
	v_pk_mul_f32 v[98:99], v[98:99], v[212:213]
	global_load_dwordx4 v[174:177], v[130:131], off offset:-2048
	global_load_dwordx4 v[178:181], v[130:131], off offset:2048
	global_load_dwordx4 v[182:185], v[130:131], off offset:-1792
	global_load_dwordx4 v[186:189], v[130:131], off offset:2304
	v_lshl_add_u64 v[130:131], v[130:131], 0, s[30:31]
	s_waitcnt vmcnt(10)
	v_lshlrev_b32_e32 v206, 16, v190
	v_and_b32_e32 v207, s63, v190
	v_lshlrev_b32_e32 v214, 16, v194
	v_and_b32_e32 v215, s63, v194
	v_lshlrev_b32_e32 v208, 16, v191
	v_and_b32_e32 v209, s63, v191
	v_lshlrev_b32_e32 v216, 16, v195
	v_and_b32_e32 v217, s63, v195
	v_lshlrev_b32_e32 v210, 16, v192
	v_and_b32_e32 v211, s63, v192
	v_lshlrev_b32_e32 v222, 16, v196
	v_and_b32_e32 v223, s63, v196
	v_lshlrev_b32_e32 v212, 16, v193
	v_and_b32_e32 v213, s63, v193
	v_lshlrev_b32_e32 v224, 16, v197
	v_and_b32_e32 v225, s63, v197
	v_max_f32_e32 v214, s62, v214
	v_max_f32_e32 v215, s62, v215
	v_max_f32_e32 v216, s62, v216
	v_max_f32_e32 v217, s62, v217
	v_max_f32_e32 v222, s62, v222
	v_max_f32_e32 v223, s62, v223
	v_max_f32_e32 v224, s62, v224
	v_max_f32_e32 v225, s62, v225
	v_rcp_f32_e32 v214, v214
	v_rcp_f32_e32 v215, v215
	v_rcp_f32_e32 v216, v216
	v_rcp_f32_e32 v217, v217
	v_rcp_f32_e32 v222, v222
	v_rcp_f32_e32 v223, v223
	v_rcp_f32_e32 v224, v224
	v_rcp_f32_e32 v225, v225
	v_max_f32_e32 v206, s62, v206
	v_max_f32_e32 v207, s62, v207
	v_max_f32_e32 v208, s62, v208
	v_max_f32_e32 v209, s62, v209
	v_max_f32_e32 v210, s62, v210
	v_max_f32_e32 v211, s62, v211
	v_max_f32_e32 v212, s62, v212
	v_max_f32_e32 v213, s62, v213
	v_pk_mul_f32 v[206:207], v[206:207], v[214:215]
	v_pk_mul_f32 v[208:209], v[208:209], v[216:217]
	v_pk_mul_f32 v[210:211], v[210:211], v[222:223]
	v_pk_mul_f32 v[212:213], v[212:213], v[224:225]
	v_pk_mul_f32 v[92:93], v[92:93], v[206:207]
	v_pk_mul_f32 v[94:95], v[94:95], v[208:209]
	v_pk_mul_f32 v[88:89], v[88:89], v[210:211]
	v_pk_mul_f32 v[90:91], v[90:91], v[212:213]
	s_waitcnt vmcnt(8)
	v_lshlrev_b32_e32 v206, 16, v198
	v_and_b32_e32 v207, s63, v198
	v_lshlrev_b32_e32 v214, 16, v202
	v_and_b32_e32 v215, s63, v202
	v_lshlrev_b32_e32 v208, 16, v199
	v_and_b32_e32 v209, s63, v199
	v_lshlrev_b32_e32 v216, 16, v203
	v_and_b32_e32 v217, s63, v203
	v_lshlrev_b32_e32 v210, 16, v200
	v_and_b32_e32 v211, s63, v200
	v_lshlrev_b32_e32 v222, 16, v204
	v_and_b32_e32 v223, s63, v204
	v_lshlrev_b32_e32 v212, 16, v201
	v_and_b32_e32 v213, s63, v201
	v_lshlrev_b32_e32 v224, 16, v205
	v_and_b32_e32 v225, s63, v205
	v_max_f32_e32 v214, s62, v214
	v_max_f32_e32 v215, s62, v215
	v_max_f32_e32 v216, s62, v216
	v_max_f32_e32 v217, s62, v217
	v_max_f32_e32 v222, s62, v222
	v_max_f32_e32 v223, s62, v223
	v_max_f32_e32 v224, s62, v224
	v_max_f32_e32 v225, s62, v225
	v_rcp_f32_e32 v214, v214
	v_rcp_f32_e32 v215, v215
	v_rcp_f32_e32 v216, v216
	v_rcp_f32_e32 v217, v217
	v_rcp_f32_e32 v222, v222
	v_rcp_f32_e32 v223, v223
	v_rcp_f32_e32 v224, v224
	v_rcp_f32_e32 v225, v225
	v_max_f32_e32 v206, s62, v206
	v_max_f32_e32 v207, s62, v207
	v_max_f32_e32 v208, s62, v208
	v_max_f32_e32 v209, s62, v209
	v_max_f32_e32 v210, s62, v210
	v_max_f32_e32 v211, s62, v211
	v_max_f32_e32 v212, s62, v212
	v_max_f32_e32 v213, s62, v213
	v_pk_mul_f32 v[206:207], v[206:207], v[214:215]
	v_pk_mul_f32 v[208:209], v[208:209], v[216:217]
	v_pk_mul_f32 v[210:211], v[210:211], v[222:223]
	v_pk_mul_f32 v[212:213], v[212:213], v[224:225]
	v_pk_mul_f32 v[84:85], v[84:85], v[206:207]
	v_pk_mul_f32 v[86:87], v[86:87], v[208:209]
	v_pk_mul_f32 v[80:81], v[80:81], v[210:211]
	v_pk_mul_f32 v[82:83], v[82:83], v[212:213]
	global_load_dwordx4 v[190:193], v[130:131], off offset:-2048
	global_load_dwordx4 v[194:197], v[130:131], off offset:2048
	global_load_dwordx4 v[198:201], v[130:131], off offset:-1792
	global_load_dwordx4 v[202:205], v[130:131], off offset:2304
	v_lshl_add_u64 v[130:131], v[130:131], 0, s[30:31]
	s_waitcnt vmcnt(10)
; DI void unpack8(const u32x4 v, float* x) { x[0] = bflo(v.x); x[1] = bfhi(v.x); x[2] = bflo(v.y); x[3] = bfhi(v.y); x[4] = bflo(v.z); x[5] = bfhi(v.z); x[6] = bflo(v.w); x[7] = bfhi(v.w); }
;     DI void hook(f32x4 (&acc)[2][2][4][2], const Unit& u, int n, int wr, int wc, int fr, int fq) const {
;         int row0 = u.pm * BM + wr * 64 + fr, col0 = u.pn * BM + wc * 32 + 8 * fq;
;         asm volatile("" : "+v"(row0), "+v"(col0));
; #pragma unroll
;         for (int ai = 0; ai < 2; ++ai) {
; #pragma unroll
;             for (int m = 0; m < 4; ++m) { const size_t row = (size_t)(row0 + ai * HALF + m * 16);
; #pragma unroll
;                 for (int bj = 0; bj < 2; ++bj) { const int col = col0 + bj * HALF;
;                     float gp[8], gc[8]; unpack8(*(const u32x4*)(G + row * LDP + (size_t)(n - 1) * DM + col), gp); unpack8(*(const u32x4*)(G + row * LDP + (size_t)n * DM + col), gc);
; #pragma unroll
;                     for (int j = 0; j < 4; ++j) { acc[ai][bj][m][0][j] *= fmaxf(gp[j], 1e-30f) * __builtin_amdgcn_rcpf(fmaxf(gc[j], 1e-30f));
;                                                   acc[ai][bj][m][1][j] *= fmaxf(gp[4 + j], 1e-30f) * __builtin_amdgcn_rcpf(fmaxf(gc[4 + j], 1e-30f)); } }
;                 if (m & 1) asm volatile("" ::: "memory"); }
	v_lshlrev_b32_e32 v206, 16, v158
	v_and_b32_e32 v207, s63, v158
	v_lshlrev_b32_e32 v214, 16, v162
	v_and_b32_e32 v215, s63, v162
	v_lshlrev_b32_e32 v208, 16, v159
	v_and_b32_e32 v209, s63, v159
	v_lshlrev_b32_e32 v216, 16, v163
	v_and_b32_e32 v217, s63, v163
	v_lshlrev_b32_e32 v210, 16, v160
	v_and_b32_e32 v211, s63, v160
	v_lshlrev_b32_e32 v222, 16, v164
	v_and_b32_e32 v223, s63, v164
	v_lshlrev_b32_e32 v212, 16, v161
	v_and_b32_e32 v213, s63, v161
	v_lshlrev_b32_e32 v224, 16, v165
	v_and_b32_e32 v225, s63, v165
	v_max_f32_e32 v214, s62, v214
	v_max_f32_e32 v215, s62, v215
	v_max_f32_e32 v216, s62, v216
	v_max_f32_e32 v217, s62, v217
	v_max_f32_e32 v222, s62, v222
	v_max_f32_e32 v223, s62, v223
	v_max_f32_e32 v224, s62, v224
	v_max_f32_e32 v225, s62, v225
	v_rcp_f32_e32 v214, v214
	v_rcp_f32_e32 v215, v215
	v_rcp_f32_e32 v216, v216
	v_rcp_f32_e32 v217, v217
	v_rcp_f32_e32 v222, v222
	v_rcp_f32_e32 v223, v223
	v_rcp_f32_e32 v224, v224
	v_rcp_f32_e32 v225, v225
	v_max_f32_e32 v206, s62, v206
	v_max_f32_e32 v207, s62, v207
	v_max_f32_e32 v208, s62, v208
	v_max_f32_e32 v209, s62, v209
	v_max_f32_e32 v210, s62, v210
	v_max_f32_e32 v211, s62, v211
	v_max_f32_e32 v212, s62, v212
	v_max_f32_e32 v213, s62, v213
	v_pk_mul_f32 v[206:207], v[206:207], v[214:215]
	v_pk_mul_f32 v[208:209], v[208:209], v[216:217]
	v_pk_mul_f32 v[210:211], v[210:211], v[222:223]
	v_pk_mul_f32 v[212:213], v[212:213], v[224:225]
	v_pk_mul_f32 v[76:77], v[76:77], v[206:207]
	v_pk_mul_f32 v[78:79], v[78:79], v[208:209]
	v_pk_mul_f32 v[72:73], v[72:73], v[210:211]
	v_pk_mul_f32 v[74:75], v[74:75], v[212:213]
	s_waitcnt vmcnt(8)
	v_lshlrev_b32_e32 v206, 16, v166
	v_and_b32_e32 v207, s63, v166
	v_lshlrev_b32_e32 v214, 16, v170
	v_and_b32_e32 v215, s63, v170
	v_lshlrev_b32_e32 v208, 16, v167
	v_and_b32_e32 v209, s63, v167
	v_lshlrev_b32_e32 v216, 16, v171
	v_and_b32_e32 v217, s63, v171
	v_lshlrev_b32_e32 v210, 16, v168
	v_and_b32_e32 v211, s63, v168
	v_lshlrev_b32_e32 v222, 16, v172
	v_and_b32_e32 v223, s63, v172
	v_lshlrev_b32_e32 v212, 16, v169
	v_and_b32_e32 v213, s63, v169
	v_lshlrev_b32_e32 v224, 16, v173
	v_and_b32_e32 v225, s63, v173
	v_max_f32_e32 v214, s62, v214
	v_max_f32_e32 v215, s62, v215
	v_max_f32_e32 v216, s62, v216
	v_max_f32_e32 v217, s62, v217
	v_max_f32_e32 v222, s62, v222
	v_max_f32_e32 v223, s62, v223
	v_max_f32_e32 v224, s62, v224
	v_max_f32_e32 v225, s62, v225
	v_rcp_f32_e32 v214, v214
	v_rcp_f32_e32 v215, v215
	v_rcp_f32_e32 v216, v216
	v_rcp_f32_e32 v217, v217
	v_rcp_f32_e32 v222, v222
	v_rcp_f32_e32 v223, v223
	v_rcp_f32_e32 v224, v224
	v_rcp_f32_e32 v225, v225
	v_max_f32_e32 v206, s62, v206
	v_max_f32_e32 v207, s62, v207
	v_max_f32_e32 v208, s62, v208
	v_max_f32_e32 v209, s62, v209
	v_max_f32_e32 v210, s62, v210
	v_max_f32_e32 v211, s62, v211
	v_max_f32_e32 v212, s62, v212
	v_max_f32_e32 v213, s62, v213
	v_pk_mul_f32 v[206:207], v[206:207], v[214:215]
	v_pk_mul_f32 v[208:209], v[208:209], v[216:217]
	v_pk_mul_f32 v[210:211], v[210:211], v[222:223]
	v_pk_mul_f32 v[212:213], v[212:213], v[224:225]
	v_pk_mul_f32 v[68:69], v[68:69], v[206:207]
	v_pk_mul_f32 v[70:71], v[70:71], v[208:209]
	v_pk_mul_f32 v[64:65], v[64:65], v[210:211]
	v_pk_mul_f32 v[66:67], v[66:67], v[212:213]
	global_load_dwordx4 v[158:161], v[130:131], off offset:-2048
	global_load_dwordx4 v[162:165], v[130:131], off offset:2048
	global_load_dwordx4 v[166:169], v[130:131], off offset:-1792
	global_load_dwordx4 v[170:173], v[130:131], off offset:2304
	v_lshl_add_u64 v[130:131], v[130:131], 0, s[30:31]
	s_waitcnt vmcnt(10)
	v_lshlrev_b32_e32 v206, 16, v174
	v_and_b32_e32 v207, s63, v174
	v_lshlrev_b32_e32 v214, 16, v178
	v_and_b32_e32 v215, s63, v178
	v_lshlrev_b32_e32 v208, 16, v175
	v_and_b32_e32 v209, s63, v175
	v_lshlrev_b32_e32 v216, 16, v179
	v_and_b32_e32 v217, s63, v179
	v_lshlrev_b32_e32 v210, 16, v176
	v_and_b32_e32 v211, s63, v176
	v_lshlrev_b32_e32 v222, 16, v180
	v_and_b32_e32 v223, s63, v180
	v_lshlrev_b32_e32 v212, 16, v177
	v_and_b32_e32 v213, s63, v177
	v_lshlrev_b32_e32 v224, 16, v181
	v_and_b32_e32 v225, s63, v181
	v_max_f32_e32 v214, s62, v214
	v_max_f32_e32 v215, s62, v215
	v_max_f32_e32 v216, s62, v216
	v_max_f32_e32 v217, s62, v217
	v_max_f32_e32 v222, s62, v222
	v_max_f32_e32 v223, s62, v223
	v_max_f32_e32 v224, s62, v224
	v_max_f32_e32 v225, s62, v225
	v_rcp_f32_e32 v214, v214
	v_rcp_f32_e32 v215, v215
	v_rcp_f32_e32 v216, v216
	v_rcp_f32_e32 v217, v217
	v_rcp_f32_e32 v222, v222
	v_rcp_f32_e32 v223, v223
	v_rcp_f32_e32 v224, v224
	v_rcp_f32_e32 v225, v225
	v_max_f32_e32 v206, s62, v206
	v_max_f32_e32 v207, s62, v207
	v_max_f32_e32 v208, s62, v208
	v_max_f32_e32 v209, s62, v209
	v_max_f32_e32 v210, s62, v210
	v_max_f32_e32 v211, s62, v211
	v_max_f32_e32 v212, s62, v212
	v_max_f32_e32 v213, s62, v213
	v_pk_mul_f32 v[206:207], v[206:207], v[214:215]
	v_pk_mul_f32 v[208:209], v[208:209], v[216:217]
	v_pk_mul_f32 v[210:211], v[210:211], v[222:223]
	v_pk_mul_f32 v[212:213], v[212:213], v[224:225]
	v_pk_mul_f32 v[60:61], v[60:61], v[206:207]
	v_pk_mul_f32 v[62:63], v[62:63], v[208:209]
	v_pk_mul_f32 v[56:57], v[56:57], v[210:211]
	v_pk_mul_f32 v[58:59], v[58:59], v[212:213]
	s_waitcnt vmcnt(8)
; DI void unpack8(const u32x4 v, float* x) { x[0] = bflo(v.x); x[1] = bfhi(v.x); x[2] = bflo(v.y); x[3] = bfhi(v.y); x[4] = bflo(v.z); x[5] = bfhi(v.z); x[6] = bflo(v.w); x[7] = bfhi(v.w); }
;     DI void hook(f32x4 (&acc)[2][2][4][2], const Unit& u, int n, int wr, int wc, int fr, int fq) const {
;         int row0 = u.pm * BM + wr * 64 + fr, col0 = u.pn * BM + wc * 32 + 8 * fq;
;         asm volatile("" : "+v"(row0), "+v"(col0));
; #pragma unroll
;         for (int ai = 0; ai < 2; ++ai) {
; #pragma unroll
;             for (int m = 0; m < 4; ++m) { const size_t row = (size_t)(row0 + ai * HALF + m * 16);
; #pragma unroll
;                 for (int bj = 0; bj < 2; ++bj) { const int col = col0 + bj * HALF;
;                     float gp[8], gc[8]; unpack8(*(const u32x4*)(G + row * LDP + (size_t)(n - 1) * DM + col), gp); unpack8(*(const u32x4*)(G + row * LDP + (size_t)n * DM + col), gc);
; #pragma unroll
;                     for (int j = 0; j < 4; ++j) { acc[ai][bj][m][0][j] *= fmaxf(gp[j], 1e-30f) * __builtin_amdgcn_rcpf(fmaxf(gc[j], 1e-30f));
;                                                   acc[ai][bj][m][1][j] *= fmaxf(gp[4 + j], 1e-30f) * __builtin_amdgcn_rcpf(fmaxf(gc[4 + j], 1e-30f)); } }
;                 if (m & 1) asm volatile("" ::: "memory"); }
	v_lshlrev_b32_e32 v206, 16, v182
	v_and_b32_e32 v207, s63, v182
	v_lshlrev_b32_e32 v214, 16, v186
	v_and_b32_e32 v215, s63, v186
	v_lshlrev_b32_e32 v208, 16, v183
	v_and_b32_e32 v209, s63, v183
	v_lshlrev_b32_e32 v216, 16, v187
	v_and_b32_e32 v217, s63, v187
	v_lshlrev_b32_e32 v210, 16, v184
	v_and_b32_e32 v211, s63, v184
	v_lshlrev_b32_e32 v222, 16, v188
	v_and_b32_e32 v223, s63, v188
	v_lshlrev_b32_e32 v212, 16, v185
	v_and_b32_e32 v213, s63, v185
	v_lshlrev_b32_e32 v224, 16, v189
	v_and_b32_e32 v225, s63, v189
	v_max_f32_e32 v214, s62, v214
	v_max_f32_e32 v215, s62, v215
	v_max_f32_e32 v216, s62, v216
	v_max_f32_e32 v217, s62, v217
	v_max_f32_e32 v222, s62, v222
	v_max_f32_e32 v223, s62, v223
	v_max_f32_e32 v224, s62, v224
	v_max_f32_e32 v225, s62, v225
	v_rcp_f32_e32 v214, v214
	v_rcp_f32_e32 v215, v215
	v_rcp_f32_e32 v216, v216
	v_rcp_f32_e32 v217, v217
	v_rcp_f32_e32 v222, v222
	v_rcp_f32_e32 v223, v223
	v_rcp_f32_e32 v224, v224
	v_rcp_f32_e32 v225, v225
	v_max_f32_e32 v206, s62, v206
	v_max_f32_e32 v207, s62, v207
	v_max_f32_e32 v208, s62, v208
	v_max_f32_e32 v209, s62, v209
	v_max_f32_e32 v210, s62, v210
	v_max_f32_e32 v211, s62, v211
	v_max_f32_e32 v212, s62, v212
	v_max_f32_e32 v213, s62, v213
	v_pk_mul_f32 v[206:207], v[206:207], v[214:215]
	v_pk_mul_f32 v[208:209], v[208:209], v[216:217]
	v_pk_mul_f32 v[210:211], v[210:211], v[222:223]
	v_pk_mul_f32 v[212:213], v[212:213], v[224:225]
	v_pk_mul_f32 v[52:53], v[52:53], v[206:207]
	v_pk_mul_f32 v[54:55], v[54:55], v[208:209]
	v_pk_mul_f32 v[48:49], v[48:49], v[210:211]
	v_pk_mul_f32 v[50:51], v[50:51], v[212:213]
	global_load_dwordx4 v[174:177], v[130:131], off offset:-2048
	global_load_dwordx4 v[178:181], v[130:131], off offset:2048
	global_load_dwordx4 v[182:185], v[130:131], off offset:-1792
	global_load_dwordx4 v[186:189], v[130:131], off offset:2304
	s_waitcnt vmcnt(10)
	v_lshlrev_b32_e32 v206, 16, v190
	v_and_b32_e32 v207, s63, v190
	v_lshlrev_b32_e32 v214, 16, v194
	v_and_b32_e32 v215, s63, v194
	v_lshlrev_b32_e32 v208, 16, v191
	v_and_b32_e32 v209, s63, v191
	v_lshlrev_b32_e32 v216, 16, v195
	v_and_b32_e32 v217, s63, v195
	v_lshlrev_b32_e32 v210, 16, v192
	v_and_b32_e32 v211, s63, v192
	v_lshlrev_b32_e32 v222, 16, v196
	v_and_b32_e32 v223, s63, v196
	v_lshlrev_b32_e32 v212, 16, v193
	v_and_b32_e32 v213, s63, v193
	v_lshlrev_b32_e32 v224, 16, v197
	v_and_b32_e32 v225, s63, v197
	v_max_f32_e32 v214, s62, v214
	v_max_f32_e32 v215, s62, v215
	v_max_f32_e32 v216, s62, v216
	v_max_f32_e32 v217, s62, v217
	v_max_f32_e32 v222, s62, v222
	v_max_f32_e32 v223, s62, v223
	v_max_f32_e32 v224, s62, v224
	v_max_f32_e32 v225, s62, v225
	v_rcp_f32_e32 v214, v214
	v_rcp_f32_e32 v215, v215
	v_rcp_f32_e32 v216, v216
	v_rcp_f32_e32 v217, v217
	v_rcp_f32_e32 v222, v222
	v_rcp_f32_e32 v223, v223
	v_rcp_f32_e32 v224, v224
	v_rcp_f32_e32 v225, v225
	v_max_f32_e32 v206, s62, v206
	v_max_f32_e32 v207, s62, v207
	v_max_f32_e32 v208, s62, v208
	v_max_f32_e32 v209, s62, v209
	v_max_f32_e32 v210, s62, v210
	v_max_f32_e32 v211, s62, v211
	v_max_f32_e32 v212, s62, v212
	v_max_f32_e32 v213, s62, v213
	v_pk_mul_f32 v[206:207], v[206:207], v[214:215]
	v_pk_mul_f32 v[208:209], v[208:209], v[216:217]
	v_pk_mul_f32 v[210:211], v[210:211], v[222:223]
	v_pk_mul_f32 v[212:213], v[212:213], v[224:225]
	v_pk_mul_f32 v[44:45], v[44:45], v[206:207]
	v_pk_mul_f32 v[46:47], v[46:47], v[208:209]
	v_pk_mul_f32 v[40:41], v[40:41], v[210:211]
	v_pk_mul_f32 v[42:43], v[42:43], v[212:213]
	s_waitcnt vmcnt(8)
	v_lshlrev_b32_e32 v206, 16, v198
	v_and_b32_e32 v207, s63, v198
	v_lshlrev_b32_e32 v214, 16, v202
	v_and_b32_e32 v215, s63, v202
	v_lshlrev_b32_e32 v208, 16, v199
	v_and_b32_e32 v209, s63, v199
	v_lshlrev_b32_e32 v216, 16, v203
	v_and_b32_e32 v217, s63, v203
	v_lshlrev_b32_e32 v210, 16, v200
	v_and_b32_e32 v211, s63, v200
	v_lshlrev_b32_e32 v222, 16, v204
	v_and_b32_e32 v223, s63, v204
	v_lshlrev_b32_e32 v212, 16, v201
	v_and_b32_e32 v213, s63, v201
	v_lshlrev_b32_e32 v224, 16, v205
	v_and_b32_e32 v225, s63, v205
	v_max_f32_e32 v214, s62, v214
	v_max_f32_e32 v215, s62, v215
	v_max_f32_e32 v216, s62, v216
	v_max_f32_e32 v217, s62, v217
	v_max_f32_e32 v222, s62, v222
	v_max_f32_e32 v223, s62, v223
	v_max_f32_e32 v224, s62, v224
	v_max_f32_e32 v225, s62, v225
	v_rcp_f32_e32 v214, v214
	v_rcp_f32_e32 v215, v215
	v_rcp_f32_e32 v216, v216
	v_rcp_f32_e32 v217, v217
	v_rcp_f32_e32 v222, v222
	v_rcp_f32_e32 v223, v223
	v_rcp_f32_e32 v224, v224
	v_rcp_f32_e32 v225, v225
	v_max_f32_e32 v206, s62, v206
	v_max_f32_e32 v207, s62, v207
	v_max_f32_e32 v208, s62, v208
	v_max_f32_e32 v209, s62, v209
	v_max_f32_e32 v210, s62, v210
	v_max_f32_e32 v211, s62, v211
	v_max_f32_e32 v212, s62, v212
	v_max_f32_e32 v213, s62, v213
	v_pk_mul_f32 v[206:207], v[206:207], v[214:215]
	v_pk_mul_f32 v[208:209], v[208:209], v[216:217]
	v_pk_mul_f32 v[210:211], v[210:211], v[222:223]
	v_pk_mul_f32 v[212:213], v[212:213], v[224:225]
	v_pk_mul_f32 v[36:37], v[36:37], v[206:207]
	v_pk_mul_f32 v[38:39], v[38:39], v[208:209]
	v_pk_mul_f32 v[32:33], v[32:33], v[210:211]
	v_pk_mul_f32 v[34:35], v[34:35], v[212:213]
	s_waitcnt vmcnt(6)
; DI void unpack8(const u32x4 v, float* x) { x[0] = bflo(v.x); x[1] = bfhi(v.x); x[2] = bflo(v.y); x[3] = bfhi(v.y); x[4] = bflo(v.z); x[5] = bfhi(v.z); x[6] = bflo(v.w); x[7] = bfhi(v.w); }
;     DI void hook(f32x4 (&acc)[2][2][4][2], const Unit& u, int n, int wr, int wc, int fr, int fq) const {
;         int row0 = u.pm * BM + wr * 64 + fr, col0 = u.pn * BM + wc * 32 + 8 * fq;
;         asm volatile("" : "+v"(row0), "+v"(col0));
; #pragma unroll
;         for (int ai = 0; ai < 2; ++ai) {
; #pragma unroll
;             for (int m = 0; m < 4; ++m) { const size_t row = (size_t)(row0 + ai * HALF + m * 16);
; #pragma unroll
;                 for (int bj = 0; bj < 2; ++bj) { const int col = col0 + bj * HALF;
;                     float gp[8], gc[8]; unpack8(*(const u32x4*)(G + row * LDP + (size_t)(n - 1) * DM + col), gp); unpack8(*(const u32x4*)(G + row * LDP + (size_t)n * DM + col), gc);
; #pragma unroll
;                     for (int j = 0; j < 4; ++j) { acc[ai][bj][m][0][j] *= fmaxf(gp[j], 1e-30f) * __builtin_amdgcn_rcpf(fmaxf(gc[j], 1e-30f));
;                                                   acc[ai][bj][m][1][j] *= fmaxf(gp[4 + j], 1e-30f) * __builtin_amdgcn_rcpf(fmaxf(gc[4 + j], 1e-30f)); } }
;                 if (m & 1) asm volatile("" ::: "memory"); }
	v_lshlrev_b32_e32 v206, 16, v158
	v_and_b32_e32 v207, s63, v158
	v_lshlrev_b32_e32 v214, 16, v162
	v_and_b32_e32 v215, s63, v162
	v_lshlrev_b32_e32 v208, 16, v159
	v_and_b32_e32 v209, s63, v159
	v_lshlrev_b32_e32 v216, 16, v163
	v_and_b32_e32 v217, s63, v163
	v_lshlrev_b32_e32 v210, 16, v160
	v_and_b32_e32 v211, s63, v160
	v_lshlrev_b32_e32 v222, 16, v164
	v_and_b32_e32 v223, s63, v164
	v_lshlrev_b32_e32 v212, 16, v161
	v_and_b32_e32 v213, s63, v161
	v_lshlrev_b32_e32 v224, 16, v165
	v_and_b32_e32 v225, s63, v165
	v_max_f32_e32 v214, s62, v214
	v_max_f32_e32 v215, s62, v215
	v_max_f32_e32 v216, s62, v216
	v_max_f32_e32 v217, s62, v217
	v_max_f32_e32 v222, s62, v222
	v_max_f32_e32 v223, s62, v223
	v_max_f32_e32 v224, s62, v224
	v_max_f32_e32 v225, s62, v225
	v_rcp_f32_e32 v214, v214
	v_rcp_f32_e32 v215, v215
	v_rcp_f32_e32 v216, v216
	v_rcp_f32_e32 v217, v217
	v_rcp_f32_e32 v222, v222
	v_rcp_f32_e32 v223, v223
	v_rcp_f32_e32 v224, v224
	v_rcp_f32_e32 v225, v225
	v_max_f32_e32 v206, s62, v206
	v_max_f32_e32 v207, s62, v207
	v_max_f32_e32 v208, s62, v208
	v_max_f32_e32 v209, s62, v209
	v_max_f32_e32 v210, s62, v210
	v_max_f32_e32 v211, s62, v211
	v_max_f32_e32 v212, s62, v212
	v_max_f32_e32 v213, s62, v213
	v_pk_mul_f32 v[206:207], v[206:207], v[214:215]
	v_pk_mul_f32 v[208:209], v[208:209], v[216:217]
	v_pk_mul_f32 v[210:211], v[210:211], v[222:223]
	v_pk_mul_f32 v[212:213], v[212:213], v[224:225]
	v_pk_mul_f32 v[28:29], v[28:29], v[206:207]
	v_pk_mul_f32 v[30:31], v[30:31], v[208:209]
	v_pk_mul_f32 v[24:25], v[24:25], v[210:211]
	v_pk_mul_f32 v[26:27], v[26:27], v[212:213]
	s_waitcnt vmcnt(4)
	v_lshlrev_b32_e32 v206, 16, v166
	v_and_b32_e32 v207, s63, v166
	v_lshlrev_b32_e32 v214, 16, v170
	v_and_b32_e32 v215, s63, v170
	v_lshlrev_b32_e32 v208, 16, v167
	v_and_b32_e32 v209, s63, v167
	v_lshlrev_b32_e32 v216, 16, v171
	v_and_b32_e32 v217, s63, v171
	v_lshlrev_b32_e32 v210, 16, v168
	v_and_b32_e32 v211, s63, v168
	v_lshlrev_b32_e32 v222, 16, v172
	v_and_b32_e32 v223, s63, v172
	v_lshlrev_b32_e32 v212, 16, v169
	v_and_b32_e32 v213, s63, v169
	v_lshlrev_b32_e32 v224, 16, v173
	v_and_b32_e32 v225, s63, v173
	v_max_f32_e32 v214, s62, v214
	v_max_f32_e32 v215, s62, v215
	v_max_f32_e32 v216, s62, v216
	v_max_f32_e32 v217, s62, v217
	v_max_f32_e32 v222, s62, v222
	v_max_f32_e32 v223, s62, v223
	v_max_f32_e32 v224, s62, v224
	v_max_f32_e32 v225, s62, v225
	v_rcp_f32_e32 v214, v214
	v_rcp_f32_e32 v215, v215
	v_rcp_f32_e32 v216, v216
	v_rcp_f32_e32 v217, v217
	v_rcp_f32_e32 v222, v222
	v_rcp_f32_e32 v223, v223
	v_rcp_f32_e32 v224, v224
	v_rcp_f32_e32 v225, v225
	v_max_f32_e32 v206, s62, v206
	v_max_f32_e32 v207, s62, v207
	v_max_f32_e32 v208, s62, v208
	v_max_f32_e32 v209, s62, v209
	v_max_f32_e32 v210, s62, v210
	v_max_f32_e32 v211, s62, v211
	v_max_f32_e32 v212, s62, v212
	v_max_f32_e32 v213, s62, v213
	v_pk_mul_f32 v[206:207], v[206:207], v[214:215]
	v_pk_mul_f32 v[208:209], v[208:209], v[216:217]
	v_pk_mul_f32 v[210:211], v[210:211], v[222:223]
	v_pk_mul_f32 v[212:213], v[212:213], v[224:225]
	v_pk_mul_f32 v[20:21], v[20:21], v[206:207]
	v_pk_mul_f32 v[22:23], v[22:23], v[208:209]
	v_pk_mul_f32 v[16:17], v[16:17], v[210:211]
	v_pk_mul_f32 v[18:19], v[18:19], v[212:213]
	s_waitcnt vmcnt(2)
	v_lshlrev_b32_e32 v206, 16, v174
	v_and_b32_e32 v207, s63, v174
	v_lshlrev_b32_e32 v214, 16, v178
	v_and_b32_e32 v215, s63, v178
	v_lshlrev_b32_e32 v208, 16, v175
	v_and_b32_e32 v209, s63, v175
	v_lshlrev_b32_e32 v216, 16, v179
	v_and_b32_e32 v217, s63, v179
	v_lshlrev_b32_e32 v210, 16, v176
	v_and_b32_e32 v211, s63, v176
	v_lshlrev_b32_e32 v222, 16, v180
	v_and_b32_e32 v223, s63, v180
	v_lshlrev_b32_e32 v212, 16, v177
	v_and_b32_e32 v213, s63, v177
	v_lshlrev_b32_e32 v224, 16, v181
	v_and_b32_e32 v225, s63, v181
	v_max_f32_e32 v214, s62, v214
	v_max_f32_e32 v215, s62, v215
	v_max_f32_e32 v216, s62, v216
	v_max_f32_e32 v217, s62, v217
	v_max_f32_e32 v222, s62, v222
	v_max_f32_e32 v223, s62, v223
	v_max_f32_e32 v224, s62, v224
	v_max_f32_e32 v225, s62, v225
	v_rcp_f32_e32 v214, v214
	v_rcp_f32_e32 v215, v215
	v_rcp_f32_e32 v216, v216
	v_rcp_f32_e32 v217, v217
	v_rcp_f32_e32 v222, v222
	v_rcp_f32_e32 v223, v223
	v_rcp_f32_e32 v224, v224
	v_rcp_f32_e32 v225, v225
	v_max_f32_e32 v206, s62, v206
	v_max_f32_e32 v207, s62, v207
	v_max_f32_e32 v208, s62, v208
	v_max_f32_e32 v209, s62, v209
	v_max_f32_e32 v210, s62, v210
	v_max_f32_e32 v211, s62, v211
	v_max_f32_e32 v212, s62, v212
	v_max_f32_e32 v213, s62, v213
	v_pk_mul_f32 v[206:207], v[206:207], v[214:215]
	v_pk_mul_f32 v[208:209], v[208:209], v[216:217]
	v_pk_mul_f32 v[210:211], v[210:211], v[222:223]
	v_pk_mul_f32 v[212:213], v[212:213], v[224:225]
	v_pk_mul_f32 v[12:13], v[12:13], v[206:207]
	v_pk_mul_f32 v[14:15], v[14:15], v[208:209]
	v_pk_mul_f32 v[8:9], v[8:9], v[210:211]
	v_pk_mul_f32 v[10:11], v[10:11], v[212:213]
	s_waitcnt vmcnt(0)
	v_lshlrev_b32_e32 v206, 16, v182
	v_and_b32_e32 v207, s63, v182
	v_lshlrev_b32_e32 v214, 16, v186
	v_and_b32_e32 v215, s63, v186
	v_lshlrev_b32_e32 v208, 16, v183
	v_and_b32_e32 v209, s63, v183
	v_lshlrev_b32_e32 v216, 16, v187
	v_and_b32_e32 v217, s63, v187
	v_lshlrev_b32_e32 v210, 16, v184
	v_and_b32_e32 v211, s63, v184
	v_lshlrev_b32_e32 v222, 16, v188
	v_and_b32_e32 v223, s63, v188
	v_lshlrev_b32_e32 v212, 16, v185
	v_and_b32_e32 v213, s63, v185
	v_lshlrev_b32_e32 v224, 16, v189
	v_and_b32_e32 v225, s63, v189
	v_max_f32_e32 v214, s62, v214
	v_max_f32_e32 v215, s62, v215
	v_max_f32_e32 v216, s62, v216
	v_max_f32_e32 v217, s62, v217
	v_max_f32_e32 v222, s62, v222
	v_max_f32_e32 v223, s62, v223
	v_max_f32_e32 v224, s62, v224
	v_max_f32_e32 v225, s62, v225
	v_rcp_f32_e32 v214, v214
	v_rcp_f32_e32 v215, v215
	v_rcp_f32_e32 v216, v216
	v_rcp_f32_e32 v217, v217
	v_rcp_f32_e32 v222, v222
	v_rcp_f32_e32 v223, v223
	v_rcp_f32_e32 v224, v224
	v_rcp_f32_e32 v225, v225
	v_max_f32_e32 v206, s62, v206
	v_max_f32_e32 v207, s62, v207
	v_max_f32_e32 v208, s62, v208
	v_max_f32_e32 v209, s62, v209
	v_max_f32_e32 v210, s62, v210
	v_max_f32_e32 v211, s62, v211
	v_max_f32_e32 v212, s62, v212
	v_max_f32_e32 v213, s62, v213
	v_pk_mul_f32 v[206:207], v[206:207], v[214:215]
	v_pk_mul_f32 v[208:209], v[208:209], v[216:217]
	v_pk_mul_f32 v[210:211], v[210:211], v[222:223]
	v_pk_mul_f32 v[212:213], v[212:213], v[224:225]
	v_pk_mul_f32 v[4:5], v[4:5], v[206:207]
	v_pk_mul_f32 v[6:7], v[6:7], v[208:209]
	v_pk_mul_f32 v[0:1], v[0:1], v[210:211]
	v_pk_mul_f32 v[2:3], v[2:3], v[212:213]
	s_branch .LBB0_712

; DI void unpack8(const u32x4 v, float* x) { x[0] = bflo(v.x); x[1] = bfhi(v.x); x[2] = bflo(v.y); x[3] = bfhi(v.y); x[4] = bflo(v.z); x[5] = bfhi(v.z); x[6] = bflo(v.w); x[7] = bfhi(v.w); }
;     DI void operator()(const f32x4 (&acc)[2][2][4][2], const Unit& u, int wr, int wc, int fr, int fq) const {
;         int row0 = u.pm * BM + wr * 64 + fr, col0 = u.pn * BM + wc * 32 + 8 * fq;
;         asm volatile("" : "+v"(row0), "+v"(col0));
; #pragma unroll
;         for (int ai = 0; ai < 2; ++ai)
; #pragma unroll
;             for (int m = 0; m < 4; ++m) { const size_t row = (size_t)(row0 + ai * HALF + m * 16);
; #pragma unroll
;                 for (int bj = 0; bj < 2; ++bj) { const int col = col0 + bj * HALF;
;                     float g[8]; unpack8(*(const u32x4*)(G + row * LDP + (size_t)3 * DM + col), g);
;                     const f32x4 v0 = acc[ai][bj][m][0], v1 = acc[ai][bj][m][1];
;                     u32x4 w; w.x = cvt_pk(v0[0] * fmaxf(g[0], 1e-30f), v0[1] * fmaxf(g[1], 1e-30f)); w.y = cvt_pk(v0[2] * fmaxf(g[2], 1e-30f), v0[3] * fmaxf(g[3], 1e-30f));
;                     w.z = cvt_pk(v1[0] * fmaxf(g[4], 1e-30f), v1[1] * fmaxf(g[5], 1e-30f)); w.w = cvt_pk(v1[2] * fmaxf(g[6], 1e-30f), v1[3] * fmaxf(g[7], 1e-30f));
;                     *(u32x4*)(MB + row * DM + col) = w; } }
.LBB0_717:
	s_add_u32 s10, s18, 0x3000
	s_addc_u32 s11, s19, 0
	s_mov_b32 s14, 0xda24260
	s_mov_b32 s29, 0xffff0000
	s_mov_b32 s30, 0x8c000
	s_mov_b32 s31, 0
	s_mov_b32 s16, 0x2bc000
	s_mov_b32 s17, 0
	v_mov_b64_e32 v[132:133], s[10:11]
	v_mad_i64_i32 v[130:131], vcc, v146, s68, v[132:133]
	v_lshlrev_b32_e32 v132, 1, v148
	v_mov_b32_e32 v133, 0
	v_lshl_add_u64 v[130:131], v[130:131], 0, v[132:133]
	global_load_dwordx4 v[158:161], v[130:131], off
	global_load_dwordx4 v[162:165], v[130:131], off offset:256
	v_lshl_add_u64 v[130:131], v[130:131], 0, s[30:31]
	global_load_dwordx4 v[166:169], v[130:131], off
	global_load_dwordx4 v[170:173], v[130:131], off offset:256
	v_lshl_add_u64 v[130:131], v[130:131], 0, s[30:31]
	global_load_dwordx4 v[174:177], v[130:131], off
	global_load_dwordx4 v[178:181], v[130:131], off offset:256
	v_lshl_add_u64 v[130:131], v[130:131], 0, s[30:31]
	global_load_dwordx4 v[182:185], v[130:131], off
	global_load_dwordx4 v[186:189], v[130:131], off offset:256
	v_lshl_add_u64 v[130:131], v[130:131], 0, s[16:17]
	global_load_dwordx4 v[190:193], v[130:131], off
	global_load_dwordx4 v[194:197], v[130:131], off offset:256
	v_lshl_add_u64 v[130:131], v[130:131], 0, s[30:31]
	global_load_dwordx4 v[198:201], v[130:131], off
	global_load_dwordx4 v[202:205], v[130:131], off offset:256
	v_lshl_add_u64 v[130:131], v[130:131], 0, s[30:31]
	global_load_dwordx4 v[206:209], v[130:131], off
	global_load_dwordx4 v[210:213], v[130:131], off offset:256
	v_lshl_add_u64 v[130:131], v[130:131], 0, s[30:31]
	global_load_dwordx4 v[214:217], v[130:131], off
	global_load_dwordx4 v[222:225], v[130:131], off offset:256
	v_lshlrev_b32_e32 v128, 12, v146
	v_add_u32_e32 v132, v128, v132
	v_lshl_add_u64 v[132:133], v[132:133], 0, s[6:7]
	s_mov_b32 s30, 0x10000
	s_mov_b32 s16, 0x50000
	s_waitcnt vmcnt(15)
	v_lshlrev_b32_e32 v150, 16, v158
	v_and_b32_e32 v151, s29, v158
	v_lshlrev_b32_e32 v152, 16, v159
	v_and_b32_e32 v153, s29, v159
	v_lshlrev_b32_e32 v226, 16, v160
	v_and_b32_e32 v227, s29, v160
	v_lshlrev_b32_e32 v130, 16, v161
	v_and_b32_e32 v131, s29, v161
	v_max_f32_e32 v150, s14, v150
	v_max_f32_e32 v151, s14, v151
	v_max_f32_e32 v152, s14, v152
	v_max_f32_e32 v153, s14, v153
	v_max_f32_e32 v226, s14, v226
	v_max_f32_e32 v227, s14, v227
	v_max_f32_e32 v130, s14, v130
	v_max_f32_e32 v131, s14, v131
	v_pk_mul_f32 v[124:125], v[124:125], v[150:151]
	v_pk_mul_f32 v[126:127], v[126:127], v[152:153]
	v_pk_mul_f32 v[120:121], v[120:121], v[226:227]
	v_pk_mul_f32 v[122:123], v[122:123], v[130:131]
	v_cvt_pk_bf16_f32 v158, v124, v125
	v_cvt_pk_bf16_f32 v159, v126, v127
	v_cvt_pk_bf16_f32 v160, v120, v121
	v_cvt_pk_bf16_f32 v161, v122, v123
	global_store_dwordx4 v[132:133], v[158:161], off
	s_waitcnt vmcnt(15)
	v_lshlrev_b32_e32 v150, 16, v162
	v_and_b32_e32 v151, s29, v162
	v_lshlrev_b32_e32 v152, 16, v163
	v_and_b32_e32 v153, s29, v163
	v_lshlrev_b32_e32 v226, 16, v164
	v_and_b32_e32 v227, s29, v164
	v_lshlrev_b32_e32 v130, 16, v165
	v_and_b32_e32 v131, s29, v165
	v_max_f32_e32 v150, s14, v150
	v_max_f32_e32 v151, s14, v151
	v_max_f32_e32 v152, s14, v152
	v_max_f32_e32 v153, s14, v153
	v_max_f32_e32 v226, s14, v226
	v_max_f32_e32 v227, s14, v227
	v_max_f32_e32 v130, s14, v130
	v_max_f32_e32 v131, s14, v131
	v_pk_mul_f32 v[116:117], v[116:117], v[150:151]
	v_pk_mul_f32 v[118:119], v[118:119], v[152:153]
	v_pk_mul_f32 v[112:113], v[112:113], v[226:227]
	v_pk_mul_f32 v[114:115], v[114:115], v[130:131]
	v_cvt_pk_bf16_f32 v162, v116, v117
	v_cvt_pk_bf16_f32 v163, v118, v119
	v_cvt_pk_bf16_f32 v164, v112, v113
	v_cvt_pk_bf16_f32 v165, v114, v115
	global_store_dwordx4 v[132:133], v[162:165], off offset:256
	v_lshl_add_u64 v[132:133], v[132:133], 0, s[30:31]
	s_waitcnt vmcnt(15)
	v_lshlrev_b32_e32 v150, 16, v166
	v_and_b32_e32 v151, s29, v166
	v_lshlrev_b32_e32 v152, 16, v167
	v_and_b32_e32 v153, s29, v167
	v_lshlrev_b32_e32 v226, 16, v168
	v_and_b32_e32 v227, s29, v168
	v_lshlrev_b32_e32 v130, 16, v169
	v_and_b32_e32 v131, s29, v169
	v_max_f32_e32 v150, s14, v150
	v_max_f32_e32 v151, s14, v151
	v_max_f32_e32 v152, s14, v152
	v_max_f32_e32 v153, s14, v153
	v_max_f32_e32 v226, s14, v226
	v_max_f32_e32 v227, s14, v227
	v_max_f32_e32 v130, s14, v130
	v_max_f32_e32 v131, s14, v131
	v_pk_mul_f32 v[108:109], v[108:109], v[150:151]
	v_pk_mul_f32 v[110:111], v[110:111], v[152:153]
	v_pk_mul_f32 v[104:105], v[104:105], v[226:227]
	v_pk_mul_f32 v[106:107], v[106:107], v[130:131]
	v_cvt_pk_bf16_f32 v166, v108, v109
	v_cvt_pk_bf16_f32 v167, v110, v111
	v_cvt_pk_bf16_f32 v168, v104, v105
	v_cvt_pk_bf16_f32 v169, v106, v107
	global_store_dwordx4 v[132:133], v[166:169], off
	s_waitcnt vmcnt(15)
	v_lshlrev_b32_e32 v150, 16, v170
	v_and_b32_e32 v151, s29, v170
	v_lshlrev_b32_e32 v152, 16, v171
	v_and_b32_e32 v153, s29, v171
	v_lshlrev_b32_e32 v226, 16, v172
	v_and_b32_e32 v227, s29, v172
	v_lshlrev_b32_e32 v130, 16, v173
	v_and_b32_e32 v131, s29, v173
	v_max_f32_e32 v150, s14, v150
	v_max_f32_e32 v151, s14, v151
	v_max_f32_e32 v152, s14, v152
	v_max_f32_e32 v153, s14, v153
	v_max_f32_e32 v226, s14, v226
	v_max_f32_e32 v227, s14, v227
	v_max_f32_e32 v130, s14, v130
	v_max_f32_e32 v131, s14, v131
	v_pk_mul_f32 v[100:101], v[100:101], v[150:151]
	v_pk_mul_f32 v[102:103], v[102:103], v[152:153]
	v_pk_mul_f32 v[96:97], v[96:97], v[226:227]
	v_pk_mul_f32 v[98:99], v[98:99], v[130:131]
	v_cvt_pk_bf16_f32 v170, v100, v101
	v_cvt_pk_bf16_f32 v171, v102, v103
	v_cvt_pk_bf16_f32 v172, v96, v97
	v_cvt_pk_bf16_f32 v173, v98, v99
	global_store_dwordx4 v[132:133], v[170:173], off offset:256
	v_lshl_add_u64 v[132:133], v[132:133], 0, s[30:31]
	s_waitcnt vmcnt(15)
; DI void unpack8(const u32x4 v, float* x) { x[0] = bflo(v.x); x[1] = bfhi(v.x); x[2] = bflo(v.y); x[3] = bfhi(v.y); x[4] = bflo(v.z); x[5] = bfhi(v.z); x[6] = bflo(v.w); x[7] = bfhi(v.w); }
;     DI void operator()(const f32x4 (&acc)[2][2][4][2], const Unit& u, int wr, int wc, int fr, int fq) const {
;         int row0 = u.pm * BM + wr * 64 + fr, col0 = u.pn * BM + wc * 32 + 8 * fq;
;         asm volatile("" : "+v"(row0), "+v"(col0));
; #pragma unroll
;         for (int ai = 0; ai < 2; ++ai)
; #pragma unroll
;             for (int m = 0; m < 4; ++m) { const size_t row = (size_t)(row0 + ai * HALF + m * 16);
; #pragma unroll
;                 for (int bj = 0; bj < 2; ++bj) { const int col = col0 + bj * HALF;
;                     float g[8]; unpack8(*(const u32x4*)(G + row * LDP + (size_t)3 * DM + col), g);
;                     const f32x4 v0 = acc[ai][bj][m][0], v1 = acc[ai][bj][m][1];
;                     u32x4 w; w.x = cvt_pk(v0[0] * fmaxf(g[0], 1e-30f), v0[1] * fmaxf(g[1], 1e-30f)); w.y = cvt_pk(v0[2] * fmaxf(g[2], 1e-30f), v0[3] * fmaxf(g[3], 1e-30f));
;                     w.z = cvt_pk(v1[0] * fmaxf(g[4], 1e-30f), v1[1] * fmaxf(g[5], 1e-30f)); w.w = cvt_pk(v1[2] * fmaxf(g[6], 1e-30f), v1[3] * fmaxf(g[7], 1e-30f));
;                     *(u32x4*)(MB + row * DM + col) = w; } }
	v_lshlrev_b32_e32 v150, 16, v174
	v_and_b32_e32 v151, s29, v174
	v_lshlrev_b32_e32 v152, 16, v175
	v_and_b32_e32 v153, s29, v175
	v_lshlrev_b32_e32 v226, 16, v176
	v_and_b32_e32 v227, s29, v176
	v_lshlrev_b32_e32 v130, 16, v177
	v_and_b32_e32 v131, s29, v177
	v_max_f32_e32 v150, s14, v150
	v_max_f32_e32 v151, s14, v151
	v_max_f32_e32 v152, s14, v152
	v_max_f32_e32 v153, s14, v153
	v_max_f32_e32 v226, s14, v226
	v_max_f32_e32 v227, s14, v227
	v_max_f32_e32 v130, s14, v130
	v_max_f32_e32 v131, s14, v131
	v_pk_mul_f32 v[92:93], v[92:93], v[150:151]
	v_pk_mul_f32 v[94:95], v[94:95], v[152:153]
	v_pk_mul_f32 v[88:89], v[88:89], v[226:227]
	v_pk_mul_f32 v[90:91], v[90:91], v[130:131]
	v_cvt_pk_bf16_f32 v174, v92, v93
	v_cvt_pk_bf16_f32 v175, v94, v95
	v_cvt_pk_bf16_f32 v176, v88, v89
	v_cvt_pk_bf16_f32 v177, v90, v91
	global_store_dwordx4 v[132:133], v[174:177], off
	s_waitcnt vmcnt(15)
	v_lshlrev_b32_e32 v150, 16, v178
	v_and_b32_e32 v151, s29, v178
	v_lshlrev_b32_e32 v152, 16, v179
	v_and_b32_e32 v153, s29, v179
	v_lshlrev_b32_e32 v226, 16, v180
	v_and_b32_e32 v227, s29, v180
	v_lshlrev_b32_e32 v130, 16, v181
	v_and_b32_e32 v131, s29, v181
	v_max_f32_e32 v150, s14, v150
	v_max_f32_e32 v151, s14, v151
	v_max_f32_e32 v152, s14, v152
	v_max_f32_e32 v153, s14, v153
	v_max_f32_e32 v226, s14, v226
	v_max_f32_e32 v227, s14, v227
	v_max_f32_e32 v130, s14, v130
	v_max_f32_e32 v131, s14, v131
	v_pk_mul_f32 v[84:85], v[84:85], v[150:151]
	v_pk_mul_f32 v[86:87], v[86:87], v[152:153]
	v_pk_mul_f32 v[80:81], v[80:81], v[226:227]
	v_pk_mul_f32 v[82:83], v[82:83], v[130:131]
	v_cvt_pk_bf16_f32 v178, v84, v85
	v_cvt_pk_bf16_f32 v179, v86, v87
	v_cvt_pk_bf16_f32 v180, v80, v81
	v_cvt_pk_bf16_f32 v181, v82, v83
	global_store_dwordx4 v[132:133], v[178:181], off offset:256
	v_lshl_add_u64 v[132:133], v[132:133], 0, s[30:31]
	s_waitcnt vmcnt(15)
	v_lshlrev_b32_e32 v150, 16, v182
	v_and_b32_e32 v151, s29, v182
	v_lshlrev_b32_e32 v152, 16, v183
	v_and_b32_e32 v153, s29, v183
	v_lshlrev_b32_e32 v226, 16, v184
	v_and_b32_e32 v227, s29, v184
	v_lshlrev_b32_e32 v130, 16, v185
	v_and_b32_e32 v131, s29, v185
	v_max_f32_e32 v150, s14, v150
	v_max_f32_e32 v151, s14, v151
	v_max_f32_e32 v152, s14, v152
	v_max_f32_e32 v153, s14, v153
	v_max_f32_e32 v226, s14, v226
	v_max_f32_e32 v227, s14, v227
	v_max_f32_e32 v130, s14, v130
	v_max_f32_e32 v131, s14, v131
	v_pk_mul_f32 v[76:77], v[76:77], v[150:151]
	v_pk_mul_f32 v[78:79], v[78:79], v[152:153]
	v_pk_mul_f32 v[72:73], v[72:73], v[226:227]
	v_pk_mul_f32 v[74:75], v[74:75], v[130:131]
	v_cvt_pk_bf16_f32 v182, v76, v77
	v_cvt_pk_bf16_f32 v183, v78, v79
	v_cvt_pk_bf16_f32 v184, v72, v73
	v_cvt_pk_bf16_f32 v185, v74, v75
	global_store_dwordx4 v[132:133], v[182:185], off
	s_waitcnt vmcnt(15)
	v_lshlrev_b32_e32 v150, 16, v186
	v_and_b32_e32 v151, s29, v186
	v_lshlrev_b32_e32 v152, 16, v187
	v_and_b32_e32 v153, s29, v187
	v_lshlrev_b32_e32 v226, 16, v188
	v_and_b32_e32 v227, s29, v188
	v_lshlrev_b32_e32 v130, 16, v189
	v_and_b32_e32 v131, s29, v189
	v_max_f32_e32 v150, s14, v150
	v_max_f32_e32 v151, s14, v151
	v_max_f32_e32 v152, s14, v152
	v_max_f32_e32 v153, s14, v153
	v_max_f32_e32 v226, s14, v226
	v_max_f32_e32 v227, s14, v227
	v_max_f32_e32 v130, s14, v130
	v_max_f32_e32 v131, s14, v131
	v_pk_mul_f32 v[68:69], v[68:69], v[150:151]
	v_pk_mul_f32 v[70:71], v[70:71], v[152:153]
	v_pk_mul_f32 v[64:65], v[64:65], v[226:227]
	v_pk_mul_f32 v[66:67], v[66:67], v[130:131]
	v_cvt_pk_bf16_f32 v186, v68, v69
	v_cvt_pk_bf16_f32 v187, v70, v71
	v_cvt_pk_bf16_f32 v188, v64, v65
	v_cvt_pk_bf16_f32 v189, v66, v67
	global_store_dwordx4 v[132:133], v[186:189], off offset:256
	v_lshl_add_u64 v[132:133], v[132:133], 0, s[16:17]
	s_waitcnt vmcnt(15)
	v_lshlrev_b32_e32 v150, 16, v190
	v_and_b32_e32 v151, s29, v190
	v_lshlrev_b32_e32 v152, 16, v191
	v_and_b32_e32 v153, s29, v191
	v_lshlrev_b32_e32 v226, 16, v192
	v_and_b32_e32 v227, s29, v192
	v_lshlrev_b32_e32 v130, 16, v193
	v_and_b32_e32 v131, s29, v193
	v_max_f32_e32 v150, s14, v150
	v_max_f32_e32 v151, s14, v151
	v_max_f32_e32 v152, s14, v152
	v_max_f32_e32 v153, s14, v153
	v_max_f32_e32 v226, s14, v226
	v_max_f32_e32 v227, s14, v227
	v_max_f32_e32 v130, s14, v130
	v_max_f32_e32 v131, s14, v131
	v_pk_mul_f32 v[60:61], v[60:61], v[150:151]
	v_pk_mul_f32 v[62:63], v[62:63], v[152:153]
	v_pk_mul_f32 v[56:57], v[56:57], v[226:227]
	v_pk_mul_f32 v[58:59], v[58:59], v[130:131]
	v_cvt_pk_bf16_f32 v190, v60, v61
	v_cvt_pk_bf16_f32 v191, v62, v63
	v_cvt_pk_bf16_f32 v192, v56, v57
	v_cvt_pk_bf16_f32 v193, v58, v59
	global_store_dwordx4 v[132:133], v[190:193], off
	s_waitcnt vmcnt(15)
	v_lshlrev_b32_e32 v150, 16, v194
	v_and_b32_e32 v151, s29, v194
	v_lshlrev_b32_e32 v152, 16, v195
	v_and_b32_e32 v153, s29, v195
	v_lshlrev_b32_e32 v226, 16, v196
	v_and_b32_e32 v227, s29, v196
	v_lshlrev_b32_e32 v130, 16, v197
	v_and_b32_e32 v131, s29, v197
	v_max_f32_e32 v150, s14, v150
	v_max_f32_e32 v151, s14, v151
	v_max_f32_e32 v152, s14, v152
	v_max_f32_e32 v153, s14, v153
	v_max_f32_e32 v226, s14, v226
	v_max_f32_e32 v227, s14, v227
	v_max_f32_e32 v130, s14, v130
	v_max_f32_e32 v131, s14, v131
	v_pk_mul_f32 v[52:53], v[52:53], v[150:151]
	v_pk_mul_f32 v[54:55], v[54:55], v[152:153]
	v_pk_mul_f32 v[48:49], v[48:49], v[226:227]
	v_pk_mul_f32 v[50:51], v[50:51], v[130:131]
	v_cvt_pk_bf16_f32 v194, v52, v53
	v_cvt_pk_bf16_f32 v195, v54, v55
	v_cvt_pk_bf16_f32 v196, v48, v49
	v_cvt_pk_bf16_f32 v197, v50, v51
	global_store_dwordx4 v[132:133], v[194:197], off offset:256
	v_lshl_add_u64 v[132:133], v[132:133], 0, s[30:31]
	s_waitcnt vmcnt(15)
; DI void unpack8(const u32x4 v, float* x) { x[0] = bflo(v.x); x[1] = bfhi(v.x); x[2] = bflo(v.y); x[3] = bfhi(v.y); x[4] = bflo(v.z); x[5] = bfhi(v.z); x[6] = bflo(v.w); x[7] = bfhi(v.w); }
;     DI void operator()(const f32x4 (&acc)[2][2][4][2], const Unit& u, int wr, int wc, int fr, int fq) const {
;         int row0 = u.pm * BM + wr * 64 + fr, col0 = u.pn * BM + wc * 32 + 8 * fq;
;         asm volatile("" : "+v"(row0), "+v"(col0));
; #pragma unroll
;         for (int ai = 0; ai < 2; ++ai)
; #pragma unroll
;             for (int m = 0; m < 4; ++m) { const size_t row = (size_t)(row0 + ai * HALF + m * 16);
; #pragma unroll
;                 for (int bj = 0; bj < 2; ++bj) { const int col = col0 + bj * HALF;
;                     float g[8]; unpack8(*(const u32x4*)(G + row * LDP + (size_t)3 * DM + col), g);
;                     const f32x4 v0 = acc[ai][bj][m][0], v1 = acc[ai][bj][m][1];
;                     u32x4 w; w.x = cvt_pk(v0[0] * fmaxf(g[0], 1e-30f), v0[1] * fmaxf(g[1], 1e-30f)); w.y = cvt_pk(v0[2] * fmaxf(g[2], 1e-30f), v0[3] * fmaxf(g[3], 1e-30f));
;                     w.z = cvt_pk(v1[0] * fmaxf(g[4], 1e-30f), v1[1] * fmaxf(g[5], 1e-30f)); w.w = cvt_pk(v1[2] * fmaxf(g[6], 1e-30f), v1[3] * fmaxf(g[7], 1e-30f));
;                     *(u32x4*)(MB + row * DM + col) = w; } }
	v_lshlrev_b32_e32 v150, 16, v198
	v_and_b32_e32 v151, s29, v198
	v_lshlrev_b32_e32 v152, 16, v199
	v_and_b32_e32 v153, s29, v199
	v_lshlrev_b32_e32 v226, 16, v200
	v_and_b32_e32 v227, s29, v200
	v_lshlrev_b32_e32 v130, 16, v201
	v_and_b32_e32 v131, s29, v201
	v_max_f32_e32 v150, s14, v150
	v_max_f32_e32 v151, s14, v151
	v_max_f32_e32 v152, s14, v152
	v_max_f32_e32 v153, s14, v153
	v_max_f32_e32 v226, s14, v226
	v_max_f32_e32 v227, s14, v227
	v_max_f32_e32 v130, s14, v130
	v_max_f32_e32 v131, s14, v131
	v_pk_mul_f32 v[44:45], v[44:45], v[150:151]
	v_pk_mul_f32 v[46:47], v[46:47], v[152:153]
	v_pk_mul_f32 v[40:41], v[40:41], v[226:227]
	v_pk_mul_f32 v[42:43], v[42:43], v[130:131]
	v_cvt_pk_bf16_f32 v198, v44, v45
	v_cvt_pk_bf16_f32 v199, v46, v47
	v_cvt_pk_bf16_f32 v200, v40, v41
	v_cvt_pk_bf16_f32 v201, v42, v43
	global_store_dwordx4 v[132:133], v[198:201], off
	s_waitcnt vmcnt(15)
	v_lshlrev_b32_e32 v150, 16, v202
	v_and_b32_e32 v151, s29, v202
	v_lshlrev_b32_e32 v152, 16, v203
	v_and_b32_e32 v153, s29, v203
	v_lshlrev_b32_e32 v226, 16, v204
	v_and_b32_e32 v227, s29, v204
	v_lshlrev_b32_e32 v130, 16, v205
	v_and_b32_e32 v131, s29, v205
	v_max_f32_e32 v150, s14, v150
	v_max_f32_e32 v151, s14, v151
	v_max_f32_e32 v152, s14, v152
	v_max_f32_e32 v153, s14, v153
	v_max_f32_e32 v226, s14, v226
	v_max_f32_e32 v227, s14, v227
	v_max_f32_e32 v130, s14, v130
	v_max_f32_e32 v131, s14, v131
	v_pk_mul_f32 v[36:37], v[36:37], v[150:151]
	v_pk_mul_f32 v[38:39], v[38:39], v[152:153]
	v_pk_mul_f32 v[32:33], v[32:33], v[226:227]
	v_pk_mul_f32 v[34:35], v[34:35], v[130:131]
	v_cvt_pk_bf16_f32 v202, v36, v37
	v_cvt_pk_bf16_f32 v203, v38, v39
	v_cvt_pk_bf16_f32 v204, v32, v33
	v_cvt_pk_bf16_f32 v205, v34, v35
	global_store_dwordx4 v[132:133], v[202:205], off offset:256
	v_lshl_add_u64 v[132:133], v[132:133], 0, s[30:31]
	s_waitcnt vmcnt(15)
	v_lshlrev_b32_e32 v150, 16, v206
	v_and_b32_e32 v151, s29, v206
	v_lshlrev_b32_e32 v152, 16, v207
	v_and_b32_e32 v153, s29, v207
	v_lshlrev_b32_e32 v226, 16, v208
	v_and_b32_e32 v227, s29, v208
	v_lshlrev_b32_e32 v130, 16, v209
	v_and_b32_e32 v131, s29, v209
	v_max_f32_e32 v150, s14, v150
	v_max_f32_e32 v151, s14, v151
	v_max_f32_e32 v152, s14, v152
	v_max_f32_e32 v153, s14, v153
	v_max_f32_e32 v226, s14, v226
	v_max_f32_e32 v227, s14, v227
	v_max_f32_e32 v130, s14, v130
	v_max_f32_e32 v131, s14, v131
	v_pk_mul_f32 v[28:29], v[28:29], v[150:151]
	v_pk_mul_f32 v[30:31], v[30:31], v[152:153]
	v_pk_mul_f32 v[24:25], v[24:25], v[226:227]
	v_pk_mul_f32 v[26:27], v[26:27], v[130:131]
	v_cvt_pk_bf16_f32 v206, v28, v29
	v_cvt_pk_bf16_f32 v207, v30, v31
	v_cvt_pk_bf16_f32 v208, v24, v25
	v_cvt_pk_bf16_f32 v209, v26, v27
	global_store_dwordx4 v[132:133], v[206:209], off
	s_waitcnt vmcnt(15)
	v_lshlrev_b32_e32 v150, 16, v210
	v_and_b32_e32 v151, s29, v210
	v_lshlrev_b32_e32 v152, 16, v211
	v_and_b32_e32 v153, s29, v211
	v_lshlrev_b32_e32 v226, 16, v212
	v_and_b32_e32 v227, s29, v212
	v_lshlrev_b32_e32 v130, 16, v213
	v_and_b32_e32 v131, s29, v213
	v_max_f32_e32 v150, s14, v150
	v_max_f32_e32 v151, s14, v151
	v_max_f32_e32 v152, s14, v152
	v_max_f32_e32 v153, s14, v153
	v_max_f32_e32 v226, s14, v226
	v_max_f32_e32 v227, s14, v227
	v_max_f32_e32 v130, s14, v130
	v_max_f32_e32 v131, s14, v131
	v_pk_mul_f32 v[20:21], v[20:21], v[150:151]
	v_pk_mul_f32 v[22:23], v[22:23], v[152:153]
	v_pk_mul_f32 v[16:17], v[16:17], v[226:227]
	v_pk_mul_f32 v[18:19], v[18:19], v[130:131]
	v_cvt_pk_bf16_f32 v210, v20, v21
	v_cvt_pk_bf16_f32 v211, v22, v23
	v_cvt_pk_bf16_f32 v212, v16, v17
	v_cvt_pk_bf16_f32 v213, v18, v19
	global_store_dwordx4 v[132:133], v[210:213], off offset:256
	v_lshl_add_u64 v[132:133], v[132:133], 0, s[30:31]
	s_waitcnt vmcnt(15)
	v_lshlrev_b32_e32 v150, 16, v214
	v_and_b32_e32 v151, s29, v214
	v_lshlrev_b32_e32 v152, 16, v215
	v_and_b32_e32 v153, s29, v215
	v_lshlrev_b32_e32 v226, 16, v216
	v_and_b32_e32 v227, s29, v216
	v_lshlrev_b32_e32 v130, 16, v217
	v_and_b32_e32 v131, s29, v217
	v_max_f32_e32 v150, s14, v150
	v_max_f32_e32 v151, s14, v151
	v_max_f32_e32 v152, s14, v152
	v_max_f32_e32 v153, s14, v153
	v_max_f32_e32 v226, s14, v226
	v_max_f32_e32 v227, s14, v227
	v_max_f32_e32 v130, s14, v130
	v_max_f32_e32 v131, s14, v131
	v_pk_mul_f32 v[12:13], v[12:13], v[150:151]
	v_pk_mul_f32 v[14:15], v[14:15], v[152:153]
	v_pk_mul_f32 v[8:9], v[8:9], v[226:227]
	v_pk_mul_f32 v[10:11], v[10:11], v[130:131]
	v_cvt_pk_bf16_f32 v214, v12, v13
	v_cvt_pk_bf16_f32 v215, v14, v15
	v_cvt_pk_bf16_f32 v216, v8, v9
	v_cvt_pk_bf16_f32 v217, v10, v11
	global_store_dwordx4 v[132:133], v[214:217], off
	s_waitcnt vmcnt(15)
	v_lshlrev_b32_e32 v150, 16, v222
	v_and_b32_e32 v151, s29, v222
	v_lshlrev_b32_e32 v152, 16, v223
	v_and_b32_e32 v153, s29, v223
	v_lshlrev_b32_e32 v226, 16, v224
	v_and_b32_e32 v227, s29, v224
	v_lshlrev_b32_e32 v130, 16, v225
	v_and_b32_e32 v131, s29, v225
	v_max_f32_e32 v150, s14, v150
	v_max_f32_e32 v151, s14, v151
	v_max_f32_e32 v152, s14, v152
	v_max_f32_e32 v153, s14, v153
	v_max_f32_e32 v226, s14, v226
	v_max_f32_e32 v227, s14, v227
	v_max_f32_e32 v130, s14, v130
	v_max_f32_e32 v131, s14, v131
	v_pk_mul_f32 v[4:5], v[4:5], v[150:151]
	v_pk_mul_f32 v[6:7], v[6:7], v[152:153]
	v_pk_mul_f32 v[0:1], v[0:1], v[226:227]
	v_pk_mul_f32 v[2:3], v[2:3], v[130:131]
	v_cvt_pk_bf16_f32 v222, v4, v5
	v_cvt_pk_bf16_f32 v223, v6, v7
	v_cvt_pk_bf16_f32 v224, v0, v1
	v_cvt_pk_bf16_f32 v225, v2, v3
	global_store_dwordx4 v[132:133], v[222:225], off offset:256
	s_mov_b64 s[8:9], -1
	s_andn2_b64 vcc, exec, s[0:1]
	s_cbranch_vccnz .LBB0_704
	s_andn2_b64 vcc, exec, s[4:5]
	s_cbranch_vccnz .LBB0_703
	s_barrier
	s_branch .LBB0_703
